# R2 retention chunk loop: LDS fragment reads issued ahead of MFMAs, prefetch addresses via scalar base, state update pipelined, next-chunk Q loads hoisted; X2 pairs rebalanced
# speedup vs baseline: 1.0671x; 1.0671x over previous
; __device__ __forceinline__ void ret_prompt_item(LAS unsigned char* lds, const bf16_t* z, bf16_t* o, float* state_out, int item, int tid) {
;     ...
;         for (int r = 0; r < 8; ++r) { const int idx = tid + 512 * r, row = idx >> 5, ch = idx & 31; kreg[r] = *(const u32x4*)(z + (tk + row) * RIN + 2048 + h * 256 + ch * 8); }
; #pragma unroll
;         for (int r = 0; r < 2; ++r) { const int idx = tid + 512 * r, row = idx >> 3, ch = idx & 7; vreg[r] = *(const u32x4*)(z + (tk + row) * RIN + 4096 + h * 512 + et * 64 + ch * 8); }
;     ...
;     for (int e4 = 0; e4 < 4; ++e4)
; #pragma unroll
;         for (int dt = 0; dt < 2; ++dt) {
; #pragma unroll
;             for (int jj = 0; jj < 4; ++jj) { const int d = 16 * (2 * wave + dt) + 4 * g + jj;
;                 state_out[((size_t)(b * 8 + h) * 256 + d) * 512 + et * 64 + 16 * e4 + l15] = accS[e4][dt][jj]; }
;         }
;     __syncthreads();
.LBB0_403:
	v_ashrrev_i32_e32 v134, 5, v145
	v_mov_b32_e32 v135, 0
	v_add_u32_e32 v136, 16, v134
	v_mov_b32_e32 v137, 0
	v_add_u32_e32 v146, 32, v134
	v_mov_b32_e32 v147, 0
	v_add_u32_e32 v148, 48, v134
	v_mov_b32_e32 v149, 0
	v_add_u32_e32 v150, 64, v134
	v_mov_b32_e32 v151, 0
	v_add_u32_e32 v152, 80, v134
	v_mov_b32_e32 v153, 0
	v_add_u32_e32 v154, 96, v134
	v_mov_b32_e32 v155, 0
	v_add_u32_e32 v156, 112, v134
	v_mov_b32_e32 v157, 0
	v_ashrrev_i32_e32 v160, 3, v145
	v_mov_b32_e32 v161, 0
	v_add_u32_e32 v162, 64, v160
	v_mov_b32_e32 v163, 0
	s_lshl_b32 s8, s8, 3
	s_or_b32 s10, s8, s30
	s_ashr_i32 s11, s10, 31
	s_lshl_b64 s[10:11], s[10:11], 19
	s_add_u32 s8, s28, s10
	s_addc_u32 s10, s29, s11
	s_lshl_b32 s9, s9, 2
	s_add_u32 s8, s8, s9
	s_addc_u32 s9, s10, 0
	v_mov_b32_e32 v189, v1
	v_lshl_add_u64 v[2:3], s[8:9], 0, v[188:189]
	s_add_i32 s54, s54, s82
	v_lshl_add_u64 v[4:5], v[2:3], 0, v[168:169]
	v_lshl_add_u64 v[6:7], v[2:3], 0, v[170:171]
	v_lshl_add_u64 v[8:9], v[2:3], 0, v[172:173]
	v_lshl_add_u64 v[10:11], v[2:3], 0, v[174:175]
	v_lshl_add_u64 v[12:13], v[2:3], 0, v[176:177]
	v_lshl_add_u64 v[14:15], v[2:3], 0, v[178:179]
	v_lshl_add_u64 v[16:17], v[2:3], 0, v[180:181]
	v_lshl_add_u64 v[2:3], v[2:3], 0, v[182:183]
	s_cmpk_gt_i32 s54, 0x7f
	global_store_dword v[4:5], v42, off
	global_store_dword v[6:7], v43, off
	global_store_dword v[8:9], v44, off
	global_store_dword v[10:11], v45, off
	global_store_dword v[12:13], v46, off
	global_store_dword v[14:15], v47, off
	global_store_dword v[16:17], v48, off
	global_store_dword v[2:3], v49, off
	global_store_dword v[4:5], v54, off offset:64
	global_store_dword v[6:7], v55, off offset:64
	global_store_dword v[8:9], v56, off offset:64
	global_store_dword v[10:11], v57, off offset:64
	global_store_dword v[12:13], v50, off offset:64
	global_store_dword v[14:15], v51, off offset:64
	global_store_dword v[16:17], v52, off offset:64
	global_store_dword v[2:3], v53, off offset:64
	global_store_dword v[4:5], v62, off offset:128
	global_store_dword v[6:7], v63, off offset:128
	global_store_dword v[8:9], v64, off offset:128
	global_store_dword v[10:11], v65, off offset:128
	global_store_dword v[12:13], v58, off offset:128
	global_store_dword v[14:15], v59, off offset:128
	global_store_dword v[16:17], v60, off offset:128
	global_store_dword v[2:3], v61, off offset:128
	global_store_dword v[4:5], v70, off offset:192
	global_store_dword v[6:7], v71, off offset:192
	global_store_dword v[8:9], v72, off offset:192
	global_store_dword v[10:11], v73, off offset:192
	global_store_dword v[12:13], v66, off offset:192
	global_store_dword v[14:15], v67, off offset:192
	global_store_dword v[16:17], v68, off offset:192
	global_store_dword v[2:3], v69, off offset:192
	s_waitcnt lgkmcnt(0)
	s_barrier
	s_cbranch_scc1 .LBB0_419

; #define LAS __attribute__((address_space(3)))
; __device__ __forceinline__ void ret_prompt_item(LAS unsigned char* lds, const bf16_t* z, bf16_t* o, float* state_out, int item, int tid) {
;     const int et = item & 7, h = (item >> 3) & 7, b = item >> 6;
;     const int wave = tid >> 6, lane = tid & 63, l15 = lane & 15, g = lane >> 4, q4 = l15 >> 2, p4 = lane & 3;
;     const float lg = log1pf(-exp2f(-5.0f - (float)h));
;     LAS unsigned char* Kn = lds;
;     LAS unsigned char* Vn = lds + 67584;
;     LAS unsigned char* Vd = Vn + 18432;
;     LAS unsigned char* St = Vd + 18432;
;     for (int idx = tid; idx < 33792 / 4; idx += NTHREADS) ((LAS unsigned*)St)[idx] = 0u;
;     f32x4 accS[4][2];
; #pragma unroll
;     for (int e4 = 0; e4 < 4; ++e4) { accS[e4][0] = (f32x4){0.f, 0.f, 0.f, 0.f}; accS[e4][1] = (f32x4){0.f, 0.f, 0.f, 0.f}; }
;     const float g128 = expf(128.0f * lg);
;     const int itw = (wave < 4) ? wave : 11 - wave;
;     const int i = 16 * itw + l15;
;     const float qd = expf((float)(i + 1) * lg);
;     const float lg2 = lg * 1.44269504089f;
;     u32x4 kreg[8], vreg[2];
;     {
;         const size_t tk = (size_t)b * SEQL;
; #pragma unroll
;         for (int r = 0; r < 8; ++r) { const int idx = tid + 512 * r, row = idx >> 5, ch = idx & 31; kreg[r] = *(const u32x4*)(z + (tk + row) * RIN + 2048 + h * 256 + ch * 8); }
; #pragma unroll
;         for (int r = 0; r < 2; ++r) { const int idx = tid + 512 * r, row = idx >> 3, ch = idx & 7; vreg[r] = *(const u32x4*)(z + (tk + row) * RIN + 4096 + h * 512 + et * 64 + ch * 8); }
.LBB0_409:
	s_or_b64 exec, exec, s[8:9]
	s_bfe_u32 s30, s24, 0x30003
	v_cvt_f32_ubyte0_e32 v0, s30
	v_sub_f32_e32 v0, 0xc0a00000, v0
	s_mov_b32 s8, 0xc2fc0000
	v_cmp_gt_f32_e32 vcc, s8, v0
	s_ashr_i32 s8, s24, 6
	s_and_b64 s[10:11], vcc, exec
	v_cndmask_b32_e32 v2, 0, v216, vcc
	v_add_f32_e32 v0, v0, v2
	v_exp_f32_e32 v0, v0
	s_cselect_b32 s9, 0xffffffc0, 0
	v_mov_b64_e32 v[34:35], s[20:21]
	s_lshl_b32 s80, s30, 10
	v_ldexp_f32 v0, v0, s9
	v_sub_f32_e32 v4, 1.0, v0
	v_add_f32_e32 v2, -1.0, v4
	v_sub_f32_e32 v3, v2, v4
	v_add_f32_e32 v3, 1.0, v3
	v_sub_f32_e64 v2, -v0, v2
	v_add_f32_e32 v5, v2, v3
	v_frexp_mant_f32_e32 v6, v4
	v_cvt_f64_f32_e32 v[2:3], v4
	s_mov_b32 s9, 0x3f2aaaab
	v_frexp_exp_i32_f64_e32 v2, v[2:3]
	v_cmp_gt_f32_e32 vcc, s9, v6
	s_mov_b32 s9, 0x3f317218
	v_lshlrev_b32_e32 v190, 1, v158
	v_subbrev_co_u32_e32 v2, vcc, 0, v2, vcc
	v_sub_u32_e32 v3, 0, v2
	v_ldexp_f32 v4, v4, v3
	v_ldexp_f32 v3, v5, v3
	v_add_f32_e32 v5, -1.0, v4
	v_add_f32_e32 v8, 1.0, v4
	v_add_f32_e32 v6, 1.0, v5
	v_add_f32_e32 v9, -1.0, v8
	v_sub_f32_e32 v6, v4, v6
	v_sub_f32_e32 v4, v4, v9
	v_add_f32_e32 v6, v3, v6
	v_add_f32_e32 v3, v3, v4
	v_add_f32_e32 v4, v8, v3
	v_rcp_f32_e32 v9, v4
	v_add_f32_e32 v7, v5, v6
	v_sub_f32_e32 v5, v7, v5
	v_sub_f32_e32 v5, v6, v5
	v_sub_f32_e32 v6, v4, v8
	v_sub_f32_e32 v3, v3, v6
	v_mul_f32_e32 v6, v7, v9
	v_mul_f32_e32 v8, v4, v6
	v_fma_f32 v10, v6, v4, -v8
	v_fmac_f32_e32 v10, v6, v3
	v_add_f32_e32 v11, v8, v10
	v_sub_f32_e32 v12, v7, v11
	v_sub_f32_e32 v7, v7, v12
	v_sub_f32_e32 v8, v11, v8
	v_sub_f32_e32 v7, v7, v11
	v_add_f32_e32 v5, v5, v7
	v_sub_f32_e32 v7, v8, v10
	v_add_f32_e32 v5, v7, v5
	v_add_f32_e32 v7, v12, v5
	v_mul_f32_e32 v8, v9, v7
	v_mul_f32_e32 v10, v4, v8
	v_fma_f32 v4, v8, v4, -v10
	v_fmac_f32_e32 v4, v8, v3
	v_sub_f32_e32 v3, v12, v7
	v_add_f32_e32 v3, v5, v3
	v_add_f32_e32 v5, v10, v4
	v_sub_f32_e32 v11, v7, v5
	v_sub_f32_e32 v7, v7, v11
	v_sub_f32_e32 v10, v5, v10
	v_sub_f32_e32 v5, v7, v5
	v_add_f32_e32 v3, v3, v5
	v_sub_f32_e32 v4, v10, v4
	v_cvt_f32_i32_e32 v2, v2
	v_add_f32_e32 v3, v4, v3
	v_add_f32_e32 v4, v6, v8
	v_add_f32_e32 v3, v11, v3
	v_sub_f32_e32 v5, v4, v6
	v_mul_f32_e32 v3, v9, v3
	v_sub_f32_e32 v5, v8, v5
	v_add_f32_e32 v3, v5, v3
	v_mul_f32_e32 v8, 0x3f317218, v2
	v_add_f32_e32 v5, v4, v3
	v_fma_f32 v9, v2, s9, -v8
	v_mul_f32_e32 v6, v5, v5
	v_fmac_f32_e32 v9, 0xb102e308, v2
	v_sub_f32_e32 v2, v5, v4
	v_fmamk_f32 v7, v6, 0x3e9b6dac, v214
	v_sub_f32_e32 v2, v3, v2
	v_add_f32_e32 v3, v8, v9
	v_fmaak_f32 v7, v6, v7, 0x3f2aaada
	v_sub_f32_e32 v4, v3, v8
	v_ldexp_f32 v8, v5, 1
	v_mul_f32_e32 v5, v5, v6
	v_mul_f32_e32 v5, v5, v7
	v_add_f32_e32 v6, v8, v5
	v_sub_f32_e32 v7, v6, v8
	v_ldexp_f32 v2, v2, 1
	v_sub_f32_e32 v5, v5, v7
	v_add_f32_e32 v2, v2, v5
	v_add_f32_e32 v5, v6, v2
	v_sub_f32_e32 v6, v5, v6
	v_sub_f32_e32 v2, v2, v6
	v_add_f32_e32 v6, v3, v5
	v_sub_f32_e32 v7, v6, v3
	v_sub_f32_e32 v8, v6, v7
	v_sub_f32_e32 v4, v9, v4
	v_sub_f32_e32 v3, v3, v8
	v_sub_f32_e32 v5, v5, v7
	v_add_f32_e32 v3, v5, v3
	v_add_f32_e32 v5, v4, v2
	v_sub_f32_e32 v7, v5, v4
	v_sub_f32_e32 v8, v5, v7
	v_sub_f32_e32 v4, v4, v8
	v_sub_f32_e32 v2, v2, v7
	v_add_f32_e32 v3, v5, v3
	v_add_f32_e32 v2, v2, v4
	v_add_f32_e32 v4, v6, v3
	v_sub_f32_e32 v5, v4, v6
	v_sub_f32_e32 v3, v3, v5
	v_add_f32_e32 v2, v2, v3
	v_add_f32_e32 v2, v4, v2
	v_cmp_nlt_f32_e32 vcc, 1.0, v0
	s_mov_b32 s9, 0x33800000
	v_mov_b32_e32 v191, v1
	v_cndmask_b32_e32 v2, v217, v2, vcc
	v_cmp_neq_f32_e32 vcc, 1.0, v0
	s_mov_b32 s34, 0x3fb8aa3b
	v_mov_b32_e32 v187, v1
	v_cndmask_b32_e32 v2, v218, v2, vcc
	v_cmp_gt_f32_e32 vcc, s9, v0
	s_ashr_i32 s9, s8, 31
	s_lshl_b64 s[10:11], s[8:9], 12
	v_cndmask_b32_e64 v43, v2, -v0, vcc
	v_lshl_add_u64 v[2:3], s[10:11], 0, v[134:135]
	v_mad_u64_u32 v[4:5], s[12:13], v2, s58, v[34:35]
	v_mad_i32_i24 v5, v3, s58, v5
	s_lshl_b32 s12, s30, 9
	s_mov_b32 s13, s81
	v_lshl_add_u64 v[2:3], v[4:5], 0, s[12:13]
	v_lshl_add_u64 v[4:5], s[10:11], 0, v[136:137]
	v_lshlrev_b32_e32 v0, 1, v132
	v_mad_u64_u32 v[6:7], s[26:27], v4, s58, v[34:35]
	v_lshl_add_u64 v[10:11], s[10:11], 0, v[146:147]
	v_lshl_add_u64 v[2:3], v[2:3], 0, v[0:1]
	v_mad_i32_i24 v7, v5, s58, v7
	v_mad_u64_u32 v[12:13], s[26:27], v10, s58, v[34:35]
	v_add_co_u32_e32 v2, vcc, s60, v2
	v_lshl_add_u64 v[4:5], v[6:7], 0, s[12:13]
	v_mad_i32_i24 v13, v11, s58, v13
	v_addc_co_u32_e32 v3, vcc, 0, v3, vcc
	v_lshl_add_u64 v[4:5], v[4:5], 0, v[0:1]
	v_lshl_add_u64 v[10:11], v[12:13], 0, s[12:13]
	v_lshl_add_u64 v[12:13], s[10:11], 0, v[148:149]
	v_add_co_u32_e32 v6, vcc, s60, v4
	v_mad_u64_u32 v[14:15], s[26:27], v12, s58, v[34:35]
	v_lshl_add_u64 v[18:19], s[10:11], 0, v[150:151]
	v_addc_co_u32_e32 v7, vcc, 0, v5, vcc
	v_lshl_add_u64 v[10:11], v[10:11], 0, v[0:1]
	v_mad_i32_i24 v15, v13, s58, v15
	v_mad_u64_u32 v[20:21], s[26:27], v18, s58, v[34:35]
	v_add_co_u32_e32 v10, vcc, s60, v10
	v_lshl_add_u64 v[12:13], v[14:15], 0, s[12:13]
	v_mad_i32_i24 v21, v19, s58, v21
	v_addc_co_u32_e32 v11, vcc, 0, v11, vcc
	v_lshl_add_u64 v[12:13], v[12:13], 0, v[0:1]
	v_lshl_add_u64 v[18:19], v[20:21], 0, s[12:13]
	v_lshl_add_u64 v[20:21], s[10:11], 0, v[152:153]
	v_add_co_u32_e32 v14, vcc, s60, v12
	v_mad_u64_u32 v[22:23], s[26:27], v20, s58, v[34:35]
	v_lshl_add_u64 v[26:27], s[10:11], 0, v[154:155]
	v_addc_co_u32_e32 v15, vcc, 0, v13, vcc
	v_lshl_add_u64 v[18:19], v[18:19], 0, v[0:1]
	v_mad_i32_i24 v23, v21, s58, v23
	v_mad_u64_u32 v[28:29], s[26:27], v26, s58, v[34:35]
	v_add_co_u32_e32 v18, vcc, s60, v18
	v_lshl_add_u64 v[20:21], v[22:23], 0, s[12:13]
	v_mad_i32_i24 v29, v27, s58, v29
	v_addc_co_u32_e32 v19, vcc, 0, v19, vcc
	v_lshl_add_u64 v[20:21], v[20:21], 0, v[0:1]
; __device__ __forceinline__ void ret_prompt_item(LAS unsigned char* lds, const bf16_t* z, bf16_t* o, float* state_out, int item, int tid) {
;     ...
;     const float g128 = expf(128.0f * lg);
;     const int itw = (wave < 4) ? wave : 11 - wave;
;     const int i = 16 * itw + l15;
;     const float qd = expf((float)(i + 1) * lg);
;     const float lg2 = lg * 1.44269504089f;
;     u32x4 kreg[8], vreg[2];
;     {
;         const size_t tk = (size_t)b * SEQL;
; #pragma unroll
;         for (int r = 0; r < 8; ++r) { const int idx = tid + 512 * r, row = idx >> 5, ch = idx & 31; kreg[r] = *(const u32x4*)(z + (tk + row) * RIN + 2048 + h * 256 + ch * 8); }
; #pragma unroll
;         for (int r = 0; r < 2; ++r) { const int idx = tid + 512 * r, row = idx >> 3, ch = idx & 7; vreg[r] = *(const u32x4*)(z + (tk + row) * RIN + 4096 + h * 512 + et * 64 + ch * 8); }
;     }
;     for (int c = 0; c < 32; ++c) {
;         const size_t tok0 = (size_t)b * SEQL + c * 128;
;         bf16x8 qf[8];
; #pragma unroll
;         for (int ks = 0; ks < 8; ++ks) qf[ks] = *(const bf16x8*)(z + (tok0 + i) * RIN + h * 256 + 32 * ks + 8 * g);
	v_lshl_add_u64 v[26:27], v[28:29], 0, s[12:13]
	v_lshl_add_u64 v[28:29], s[10:11], 0, v[156:157]
	v_lshl_add_u64 v[36:37], s[10:11], 0, v[160:161]
	v_add_co_u32_e32 v22, vcc, s60, v20
	v_mad_u64_u32 v[30:31], s[26:27], v28, s58, v[34:35]
	s_lshl_b32 s9, s24, 6
	v_mad_u64_u32 v[38:39], s[24:25], v36, s58, v[34:35]
	v_addc_co_u32_e32 v23, vcc, 0, v21, vcc
	v_lshl_add_u64 v[26:27], v[26:27], 0, v[0:1]
	v_mad_i32_i24 v31, v29, s58, v31
	v_mad_i32_i24 v39, v37, s58, v39
	v_add_co_u32_e32 v26, vcc, s60, v26
	v_lshl_add_u64 v[28:29], v[30:31], 0, s[12:13]
	s_and_b32 s9, s9, 0x1c0
	v_lshl_add_u64 v[36:37], v[38:39], 0, s[80:81]
	v_lshl_add_u64 v[38:39], s[10:11], 0, v[162:163]
	v_addc_co_u32_e32 v27, vcc, 0, v27, vcc
	v_lshl_add_u64 v[28:29], v[28:29], 0, v[0:1]
	s_lshl_b32 s24, s9, 1
	s_mov_b32 s25, s81
	v_mad_u64_u32 v[34:35], s[26:27], v38, s58, v[34:35]
	v_add_co_u32_e32 v30, vcc, s60, v28
	v_lshl_add_u64 v[36:37], v[36:37], 0, s[24:25]
	v_mad_i32_i24 v35, v39, s58, v35
	v_addc_co_u32_e32 v31, vcc, 0, v29, vcc
	v_lshl_add_u64 v[36:37], v[36:37], 0, v[190:191]
	v_lshl_add_u64 v[34:35], v[34:35], 0, s[80:81]
	v_add_co_u32_e32 v36, vcc, s33, v36
	v_lshl_add_u64 v[34:35], v[34:35], 0, s[24:25]
	s_nop 0
	v_addc_co_u32_e32 v37, vcc, 0, v37, vcc
	v_lshl_add_u64 v[34:35], v[34:35], 0, v[190:191]
	v_add_co_u32_e32 v38, vcc, s33, v34
	global_load_dwordx4 v[2:5], v[2:3], off
	s_nop 0
	global_load_dwordx4 v[6:9], v[6:7], off
	v_addc_co_u32_e32 v39, vcc, 0, v35, vcc
	global_load_dwordx4 v[10:13], v[10:11], off
	s_nop 0
	global_load_dwordx4 v[14:17], v[14:15], off
	s_nop 0
	global_load_dwordx4 v[18:21], v[18:19], off
	s_nop 0
	global_load_dwordx4 v[22:25], v[22:23], off
	s_nop 0
	global_load_dwordx4 v[26:29], v[26:27], off
	s_nop 0
	global_load_dwordx4 v[30:33], v[30:31], off
	s_nop 0
	global_load_dwordx4 v[34:37], v[36:37], off
	s_nop 0
	global_load_dwordx4 v[38:41], v[38:39], off
	v_mul_f32_e32 v44, v43, v167
	v_mul_f32_e32 v42, 0x3fb8aa3b, v44
	v_fma_f32 v45, v44, s34, -v42
	v_rndne_f32_e32 v46, v42
	v_fmac_f32_e32 v45, 0x32a5705f, v44
	v_sub_f32_e32 v42, v42, v46
	v_add_f32_e32 v42, v42, v45
	v_exp_f32_e32 v45, v42
	v_cvt_i32_f32_e32 v46, v46
	v_mul_f32_e32 v47, 0x43000000, v43
	v_mul_f32_e32 v189, 0x3fb8aa3b, v43
	s_mov_b32 s25, 0xc2ce8ed0
	v_ldexp_f32 v45, v45, v46
	v_mul_f32_e32 v46, 0x3fb8aa3b, v47
	v_fma_f32 v48, v47, s34, -v46
	v_rndne_f32_e32 v49, v46
	v_fmac_f32_e32 v48, 0x32a5705f, v47
	v_sub_f32_e32 v46, v46, v49
	v_add_f32_e32 v46, v46, v48
	v_exp_f32_e32 v46, v46
	v_cvt_i32_f32_e32 v48, v49
	v_mul_f32_e32 v43, v189, v227
	v_cmp_ngt_f32_e32 vcc, s25, v44
	s_mov_b32 s27, 0x42b17218
	s_lshl_b32 s26, s30, 8
	v_exp_f32_e32 v202, v43
	v_mul_f32_e32 v43, v189, v229
	v_cndmask_b32_e32 v45, 0, v45, vcc
	v_cmp_nlt_f32_e32 vcc, s27, v44
	v_lshl_add_u64 v[196:197], v[164:165], 0, s[12:13]
	s_add_u32 s13, s22, s80
	v_exp_f32_e32 v204, v43
	v_cndmask_b32_e32 v192, v219, v45, vcc
	v_ldexp_f32 v44, v46, v48
	v_cmp_ngt_f32_e32 vcc, s25, v47
	s_addc_u32 s25, s23, 0
	s_add_u32 s24, s13, s24
	v_cndmask_b32_e32 v44, 0, v44, vcc
	v_cmp_nlt_f32_e32 vcc, s27, v47
	v_mov_b32_e32 v42, 0
	s_addc_u32 s25, s25, 0
	v_cndmask_b32_e32 v194, v219, v44, vcc
	s_mov_b32 s31, 0
	v_mov_b32_e32 v193, v192
	v_mov_b32_e32 v198, v192
	v_mov_b32_e32 v199, v192
	v_lshl_add_u64 v[200:201], s[24:25], 0, v[186:187]
	v_mov_b32_e32 v206, v194
	v_mov_b32_e32 v207, v194
	v_mov_b32_e32 v203, v202
	v_mov_b32_e32 v205, v204
	s_lshl_b32 s80, s26, 1
	s_lshl_b32 s12, s12, 1
	v_mov_b32_e32 v43, v42
	v_mov_b32_e32 v44, v42
	v_mov_b32_e32 v45, v42
	v_mov_b32_e32 v46, v42
	v_mov_b32_e32 v47, v42
	v_mov_b32_e32 v48, v42
	v_mov_b32_e32 v49, v42
	v_mov_b32_e32 v54, v42
	v_mov_b32_e32 v55, v42
	v_mov_b32_e32 v56, v42
	v_mov_b32_e32 v57, v42
	v_mov_b32_e32 v50, v42
	v_mov_b32_e32 v51, v42
	v_mov_b32_e32 v52, v42
	v_mov_b32_e32 v53, v42
	v_mov_b32_e32 v62, v42
	v_mov_b32_e32 v63, v42
	v_mov_b32_e32 v64, v42
	v_mov_b32_e32 v65, v42
	v_mov_b32_e32 v58, v42
	v_mov_b32_e32 v59, v42
	v_mov_b32_e32 v60, v42
	v_mov_b32_e32 v61, v42
	v_mov_b32_e32 v70, v42
	v_mov_b32_e32 v71, v42
	v_mov_b32_e32 v72, v42
	v_mov_b32_e32 v73, v42
	v_mov_b32_e32 v66, v42
	v_mov_b32_e32 v67, v42
	v_mov_b32_e32 v68, v42
	v_mov_b32_e32 v69, v42
	v_mul_u32_u24_e32 v163, 0x6000, v160
	v_lshl_add_u32 v163, v158, 1, v163
	v_mul_u32_u24_e32 v162, 0x6000, v134
	v_lshl_add_u32 v162, v132, 1, v162
	s_branch .LBB0_411
.LBB0_410:
	s_cmp_eq_u32 s31, 31
	s_cbranch_scc1 .Lret_noq
	s_add_i32 s13, s31, 1
	s_lshl_b32 s13, s13, 7
	s_or_b32 s13, s10, s13
	v_add_u32_e32 v102, s13, v130
	v_mad_u64_u32 v[102:103], s[26:27], v102, s58, v[196:197]
	global_load_dwordx4 v[74:77], v[102:103], off
	global_load_dwordx4 v[78:81], v[102:103], off offset:64
	global_load_dwordx4 v[82:85], v[102:103], off offset:128
	global_load_dwordx4 v[86:89], v[102:103], off offset:192
	global_load_dwordx4 v[90:93], v[102:103], off offset:256
	global_load_dwordx4 v[94:97], v[102:103], off offset:320
	global_load_dwordx4 v[98:101], v[102:103], off offset:384
	s_nop 0
	global_load_dwordx4 v[102:105], v[102:103], off offset:448
; #define LAS __attribute__((address_space(3)))
; #define MFMA16(a, b, c) __builtin_amdgcn_mfma_f32_16x16x32_bf16((a), (b), (c), 0, 0, 0)
; __device__ __forceinline__ unsigned pk2(float lo, float hi) { return pg8::cvt_pk_bf16(lo, hi); }
; __device__ __forceinline__ void ret_prompt_item(LAS unsigned char* lds, const bf16_t* z, bf16_t* o, float* state_out, int item, int tid) {
;     ...
; #pragma unroll
;         for (int e4 = 0; e4 < 4; ++e4) {
;             u32x2 w; w.x = pk2(ao[e4][0], ao[e4][1]); w.y = pk2(ao[e4][2], ao[e4][3]);
;             *(u32x2*)(o + (tok0 + i) * 4096 + h * 512 + et * 64 + 16 * e4 + 4 * g) = w;
;         }
;         __syncthreads();
; #pragma unroll
;         for (int e4 = 0; e4 < 4; ++e4) { accS[e4][0] = accS[e4][0] * g128; accS[e4][1] = accS[e4][1] * g128; }
; #pragma unroll
;         for (int ks = 0; ks < 4; ++ks) {
;             bf16x8 kb[2];
; #pragma unroll
;             for (int dt = 0; dt < 2; ++dt) { LAS unsigned char* bp = Kn + (32 * ks + 8 * g + q4) * 528 + (16 * (2 * wave + dt) + 4 * p4) * 2; kb[dt] = tr_read8(bp, bp + 4 * 528); }
; #pragma unroll
;             for (int e4 = 0; e4 < 4; ++e4) {
;                 LAS unsigned char* ap = Vd + (32 * ks + 8 * g + q4) * 144 + (16 * e4 + 4 * p4) * 2;
;                 const bf16x8 va = tr_read8(ap, ap + 4 * 144);
;                 accS[e4][0] = MFMA16(kb[0], va, accS[e4][0]); accS[e4][1] = MFMA16(kb[1], va, accS[e4][1]);
;             }
;         }
.Lret_noq:
	v_lshlrev_b64 v[122:123], 13, v[208:209]
	v_lshl_add_u64 v[122:123], v[200:201], 0, v[122:123]
	v_cvt_pk_bf16_f32 v124, v106, v107
	v_cvt_pk_bf16_f32 v125, v108, v109
	global_store_dwordx2 v[122:123], v[124:125], off
	v_cvt_pk_bf16_f32 v124, v110, v111
	v_cvt_pk_bf16_f32 v125, v112, v113
	global_store_dwordx2 v[122:123], v[124:125], off offset:32
	v_cvt_pk_bf16_f32 v124, v114, v115
	v_cvt_pk_bf16_f32 v125, v116, v117
	global_store_dwordx2 v[122:123], v[124:125], off offset:64
	v_cvt_pk_bf16_f32 v124, v118, v119
	v_cvt_pk_bf16_f32 v125, v120, v121
	v_mov_b32_e32 v195, v194
	global_store_dwordx2 v[122:123], v[124:125], off offset:96
	s_barrier
	s_add_i32 s31, s31, 1
	v_pk_mul_f32 v[42:43], v[206:207], v[42:43]
	v_pk_mul_f32 v[44:45], v[194:195], v[44:45]
	v_pk_mul_f32 v[46:47], v[206:207], v[46:47]
	v_pk_mul_f32 v[48:49], v[194:195], v[48:49]
	v_pk_mul_f32 v[54:55], v[206:207], v[54:55]
	v_pk_mul_f32 v[56:57], v[194:195], v[56:57]
	v_pk_mul_f32 v[50:51], v[206:207], v[50:51]
	v_pk_mul_f32 v[52:53], v[194:195], v[52:53]
	v_pk_mul_f32 v[62:63], v[206:207], v[62:63]
	v_pk_mul_f32 v[64:65], v[194:195], v[64:65]
	v_pk_mul_f32 v[58:59], v[206:207], v[58:59]
	v_pk_mul_f32 v[60:61], v[194:195], v[60:61]
	v_pk_mul_f32 v[70:71], v[206:207], v[70:71]
	v_pk_mul_f32 v[72:73], v[194:195], v[72:73]
	v_pk_mul_f32 v[66:67], v[206:207], v[66:67]
	v_pk_mul_f32 v[68:69], v[194:195], v[68:69]
	ds_read_b64_tr_b16 v[106:107], v242
	ds_read_b64_tr_b16 v[108:109], v242 offset:2112
	ds_read_b64_tr_b16 v[110:111], v242 offset:32
	ds_read_b64_tr_b16 v[112:113], v242 offset:2144
	ds_read_b64_tr_b16 v[122:123], v243
	ds_read_b64_tr_b16 v[124:125], v243 offset:576
	ds_read_b64_tr_b16 v[126:127], v243 offset:32
	ds_read_b64_tr_b16 v[128:129], v243 offset:608
	ds_read_b64_tr_b16 v[246:247], v243 offset:64
	ds_read_b64_tr_b16 v[248:249], v243 offset:640
	ds_read_b64_tr_b16 v[250:251], v243 offset:96
	ds_read_b64_tr_b16 v[252:253], v243 offset:672
	ds_read_b64_tr_b16 v[114:115], v242 offset:16896
	ds_read_b64_tr_b16 v[116:117], v242 offset:19008
	ds_read_b64_tr_b16 v[118:119], v242 offset:16928
	ds_read_b64_tr_b16 v[120:121], v242 offset:19040
	ds_read_b64_tr_b16 v[134:135], v243 offset:4608
	ds_read_b64_tr_b16 v[136:137], v243 offset:5184
	s_waitcnt lgkmcnt(12)
	v_mfma_f32_16x16x32_bf16 v[42:45], v[106:109], v[122:125], v[42:45]
	v_mfma_f32_16x16x32_bf16 v[46:49], v[110:113], v[122:125], v[46:49]
	ds_read_b64_tr_b16 v[146:147], v243 offset:4640
	ds_read_b64_tr_b16 v[148:149], v243 offset:5216
	s_waitcnt lgkmcnt(12)
	v_mfma_f32_16x16x32_bf16 v[54:57], v[106:109], v[126:129], v[54:57]
	v_mfma_f32_16x16x32_bf16 v[50:53], v[110:113], v[126:129], v[50:53]
	ds_read_b64_tr_b16 v[150:151], v243 offset:4672
	ds_read_b64_tr_b16 v[152:153], v243 offset:5248
	s_waitcnt lgkmcnt(12)
	v_mfma_f32_16x16x32_bf16 v[62:65], v[106:109], v[246:249], v[62:65]
	v_mfma_f32_16x16x32_bf16 v[58:61], v[110:113], v[246:249], v[58:61]
	ds_read_b64_tr_b16 v[122:123], v243 offset:4704
	ds_read_b64_tr_b16 v[124:125], v243 offset:5280
	s_waitcnt lgkmcnt(12)
	v_mfma_f32_16x16x32_bf16 v[70:73], v[106:109], v[250:253], v[70:73]
	v_mfma_f32_16x16x32_bf16 v[66:69], v[110:113], v[250:253], v[66:69]
	ds_read_b64_tr_b16 v[106:107], v242 offset:33792
	ds_read_b64_tr_b16 v[108:109], v242 offset:35904
	ds_read_b64_tr_b16 v[110:111], v242 offset:33824
	ds_read_b64_tr_b16 v[112:113], v242 offset:35936
	ds_read_b64_tr_b16 v[126:127], v243 offset:9216
	ds_read_b64_tr_b16 v[128:129], v243 offset:9792
	s_waitcnt lgkmcnt(12)
	v_mfma_f32_16x16x32_bf16 v[42:45], v[114:117], v[134:137], v[42:45]
	v_mfma_f32_16x16x32_bf16 v[46:49], v[118:121], v[134:137], v[46:49]
	ds_read_b64_tr_b16 v[246:247], v243 offset:9248
	ds_read_b64_tr_b16 v[248:249], v243 offset:9824
	s_waitcnt lgkmcnt(12)
	v_mfma_f32_16x16x32_bf16 v[54:57], v[114:117], v[146:149], v[54:57]
	v_mfma_f32_16x16x32_bf16 v[50:53], v[118:121], v[146:149], v[50:53]
	ds_read_b64_tr_b16 v[250:251], v243 offset:9280
	ds_read_b64_tr_b16 v[252:253], v243 offset:9856
	s_waitcnt lgkmcnt(12)
	v_mfma_f32_16x16x32_bf16 v[62:65], v[114:117], v[150:153], v[62:65]
	v_mfma_f32_16x16x32_bf16 v[58:61], v[118:121], v[150:153], v[58:61]
	ds_read_b64_tr_b16 v[134:135], v243 offset:9312
	ds_read_b64_tr_b16 v[136:137], v243 offset:9888
	s_waitcnt lgkmcnt(12)
	v_mfma_f32_16x16x32_bf16 v[70:73], v[114:117], v[122:125], v[70:73]
	v_mfma_f32_16x16x32_bf16 v[66:69], v[118:121], v[122:125], v[66:69]
	ds_read_b64_tr_b16 v[114:115], v242 offset:50688
	ds_read_b64_tr_b16 v[116:117], v242 offset:52800
	ds_read_b64_tr_b16 v[118:119], v242 offset:50720
	ds_read_b64_tr_b16 v[120:121], v242 offset:52832
	ds_read_b64_tr_b16 v[146:147], v243 offset:13824
	ds_read_b64_tr_b16 v[148:149], v243 offset:14400
	s_waitcnt lgkmcnt(12)
	v_mfma_f32_16x16x32_bf16 v[42:45], v[106:109], v[126:129], v[42:45]
	v_mfma_f32_16x16x32_bf16 v[46:49], v[110:113], v[126:129], v[46:49]
	ds_read_b64_tr_b16 v[150:151], v243 offset:13856
	ds_read_b64_tr_b16 v[152:153], v243 offset:14432
	s_waitcnt lgkmcnt(12)
	v_mfma_f32_16x16x32_bf16 v[54:57], v[106:109], v[246:249], v[54:57]
	v_mfma_f32_16x16x32_bf16 v[50:53], v[110:113], v[246:249], v[50:53]
	ds_read_b64_tr_b16 v[122:123], v243 offset:13888
	ds_read_b64_tr_b16 v[124:125], v243 offset:14464
	s_waitcnt lgkmcnt(12)
	v_mfma_f32_16x16x32_bf16 v[62:65], v[106:109], v[250:253], v[62:65]
	v_mfma_f32_16x16x32_bf16 v[58:61], v[110:113], v[250:253], v[58:61]
	ds_read_b64_tr_b16 v[126:127], v243 offset:13920
	ds_read_b64_tr_b16 v[128:129], v243 offset:14496
	s_waitcnt lgkmcnt(12)
	v_mfma_f32_16x16x32_bf16 v[70:73], v[106:109], v[134:137], v[70:73]
	v_mfma_f32_16x16x32_bf16 v[66:69], v[110:113], v[134:137], v[66:69]
	s_waitcnt lgkmcnt(6)
; #define LAS __attribute__((address_space(3)))
; __device__ __forceinline__ float bf_lo(unsigned w) { return __uint_as_float(w << 16); }
; __device__ __forceinline__ float bf_hi(unsigned w) { return __uint_as_float(w & 0xffff0000u); }
; __device__ __forceinline__ unsigned pk2(float lo, float hi) { return pg8::cvt_pk_bf16(lo, hi); }
; __device__ __forceinline__ void ret_prompt_item(LAS unsigned char* lds, const bf16_t* z, bf16_t* o, float* state_out, int item, int tid) {
;     ...
;     for (int c = 0; c < 32; ++c) {
;         const size_t tok0 = (size_t)b * SEQL + c * 128;
;         bf16x8 qf[8];
; #pragma unroll
;         for (int ks = 0; ks < 8; ++ks) qf[ks] = *(const bf16x8*)(z + (tok0 + i) * RIN + h * 256 + 32 * ks + 8 * g);
;         __syncthreads();
; #pragma unroll
;         for (int r = 0; r < 8; ++r) { const int idx = tid + 512 * r, row = idx >> 5, ch = idx & 31; *(LAS u32x4*)(Kn + row * 528 + ch * 16) = kreg[r]; }
; #pragma unroll
;         for (int r = 0; r < 2; ++r) {
;             const int idx = tid + 512 * r, row = idx >> 3, ch = idx & 7;
;             const u32x4 v = vreg[r];
;             *(LAS u32x4*)(Vn + row * 144 + ch * 16) = v;
;             const float dec = __builtin_amdgcn_exp2f((float)(127 - row) * lg2);
;             u32x4 w; w.x = pk2(bf_lo(v.x) * dec, bf_hi(v.x) * dec); w.y = pk2(bf_lo(v.y) * dec, bf_hi(v.y) * dec);
;             w.z = pk2(bf_lo(v.z) * dec, bf_hi(v.z) * dec); w.w = pk2(bf_lo(v.w) * dec, bf_hi(v.w) * dec);
;             *(LAS u32x4*)(Vd + row * 144 + ch * 16) = w;
;         }
;         __syncthreads();
;     ...
; #pragma unroll
;         for (int e4 = 0; e4 < 4; ++e4)
; #pragma unroll
;             for (int dt = 0; dt < 2; ++dt)
;             { u32x2 w; w.x = pk2(accS[e4][dt][0], accS[e4][dt][1]); w.y = pk2(accS[e4][dt][2], accS[e4][dt][3]);
;                 *(LAS u32x2*)(St + (16 * e4 + l15) * 528 + (16 * (2 * wave + dt) + 4 * g) * 2) = w; }
	v_mfma_f32_16x16x32_bf16 v[42:45], v[114:117], v[146:149], v[42:45]
	v_mfma_f32_16x16x32_bf16 v[46:49], v[118:121], v[146:149], v[46:49]
	s_waitcnt lgkmcnt(4)
	v_mfma_f32_16x16x32_bf16 v[54:57], v[114:117], v[150:153], v[54:57]
	v_mfma_f32_16x16x32_bf16 v[50:53], v[118:121], v[150:153], v[50:53]
	s_waitcnt lgkmcnt(2)
	v_mfma_f32_16x16x32_bf16 v[62:65], v[114:117], v[122:125], v[62:65]
	v_mfma_f32_16x16x32_bf16 v[58:61], v[118:121], v[122:125], v[58:61]
	s_waitcnt lgkmcnt(0)
	v_mfma_f32_16x16x32_bf16 v[70:73], v[114:117], v[126:129], v[70:73]
	v_mfma_f32_16x16x32_bf16 v[66:69], v[118:121], v[126:129], v[66:69]
	s_nop 7
	v_cvt_pk_bf16_f32 v106, v42, v43
	v_cvt_pk_bf16_f32 v107, v44, v45
	v_cvt_pk_bf16_f32 v108, v46, v47
	v_cvt_pk_bf16_f32 v109, v48, v49
	ds_write2_b64 v244, v[106:107], v[108:109] offset1:4
	v_add_u32_e32 v110, 0x2000, v244
	v_cvt_pk_bf16_f32 v106, v54, v55
	v_cvt_pk_bf16_f32 v107, v56, v57
	v_cvt_pk_bf16_f32 v108, v50, v51
	v_cvt_pk_bf16_f32 v109, v52, v53
	ds_write2_b64 v110, v[106:107], v[108:109] offset0:32 offset1:36
	v_add_u32_e32 v110, 0x4000, v244
	v_cvt_pk_bf16_f32 v106, v62, v63
	v_cvt_pk_bf16_f32 v107, v64, v65
	v_cvt_pk_bf16_f32 v108, v58, v59
	v_cvt_pk_bf16_f32 v109, v60, v61
	ds_write2_b64 v110, v[106:107], v[108:109] offset0:64 offset1:68
	v_add_u32_e32 v110, 0x6000, v244
	v_cvt_pk_bf16_f32 v106, v70, v71
	v_cvt_pk_bf16_f32 v107, v72, v73
	v_cvt_pk_bf16_f32 v108, v66, v67
	v_cvt_pk_bf16_f32 v109, v68, v69
	ds_write2_b64 v110, v[106:107], v[108:109] offset0:96 offset1:100
	s_cmp_eq_u32 s31, 32
	s_cbranch_scc1 .LBB0_403
.LBB0_411:
	s_lshl_b32 s13, s31, 7
	s_or_b32 s24, s10, s13
	s_mov_b32 s25, s11
	v_lshl_add_u64 v[208:209], s[24:25], 0, v[130:131]
	s_cmp_lg_u32 s31, 0
	s_cbranch_scc1 .Lret_skipq
	v_mad_u64_u32 v[102:103], s[26:27], v208, s58, v[196:197]
	v_mad_i32_i24 v103, v209, s58, v103
	global_load_dwordx4 v[74:77], v[102:103], off
	global_load_dwordx4 v[78:81], v[102:103], off offset:64
	global_load_dwordx4 v[82:85], v[102:103], off offset:128
	global_load_dwordx4 v[86:89], v[102:103], off offset:192
	global_load_dwordx4 v[90:93], v[102:103], off offset:256
	global_load_dwordx4 v[94:97], v[102:103], off offset:320
	global_load_dwordx4 v[98:101], v[102:103], off offset:384
	s_nop 0
	global_load_dwordx4 v[102:105], v[102:103], off offset:448
.Lret_skipq:
	v_add_u32_e32 v106, v185, v226
	s_waitcnt lgkmcnt(0)
	s_barrier
	s_waitcnt vmcnt(17)
	ds_write_b128 v233, v[2:5]
	s_waitcnt vmcnt(16)
	ds_write_b128 v234, v[6:9]
	s_waitcnt vmcnt(15)
	ds_write_b128 v235, v[10:13]
	s_waitcnt vmcnt(14)
	ds_write_b128 v236, v[14:17]
	s_waitcnt vmcnt(13)
	ds_write_b128 v237, v[18:21]
	s_waitcnt vmcnt(12)
	ds_write_b128 v238, v[22:25]
	s_waitcnt vmcnt(11)
	ds_write_b128 v239, v[26:29]
	s_waitcnt vmcnt(10)
	ds_write_b128 v240, v[30:33]
	s_waitcnt vmcnt(9)
	ds_write_b128 v106, v[34:37]
	v_lshlrev_b32_e32 v106, 16, v34
	v_and_b32_e32 v107, 0xffff0000, v34
	v_lshlrev_b32_e32 v108, 16, v35
	v_and_b32_e32 v109, 0xffff0000, v35
	v_pk_mul_f32 v[106:107], v[202:203], v[106:107]
	v_pk_mul_f32 v[108:109], v[202:203], v[108:109]
	v_cvt_pk_bf16_f32 v106, v106, v107
	v_cvt_pk_bf16_f32 v107, v108, v109
	v_lshlrev_b32_e32 v108, 16, v36
	v_and_b32_e32 v109, 0xffff0000, v36
	v_lshlrev_b32_e32 v110, 16, v37
	v_and_b32_e32 v111, 0xffff0000, v37
	v_pk_mul_f32 v[108:109], v[202:203], v[108:109]
	v_pk_mul_f32 v[110:111], v[202:203], v[110:111]
	v_cvt_pk_bf16_f32 v108, v108, v109
	v_cvt_pk_bf16_f32 v109, v110, v111
	v_add_u32_e32 v110, v225, v226
	ds_write_b128 v110, v[106:109]
	v_add_u32_e32 v106, v185, v228
	s_waitcnt vmcnt(8)
	ds_write_b128 v106, v[38:41]
	v_lshlrev_b32_e32 v106, 16, v38
	v_and_b32_e32 v107, 0xffff0000, v38
	v_lshlrev_b32_e32 v108, 16, v39
	v_and_b32_e32 v109, 0xffff0000, v39
	v_pk_mul_f32 v[106:107], v[204:205], v[106:107]
	v_pk_mul_f32 v[108:109], v[204:205], v[108:109]
	v_cvt_pk_bf16_f32 v106, v106, v107
	v_cvt_pk_bf16_f32 v107, v108, v109
	v_lshlrev_b32_e32 v108, 16, v40
	v_and_b32_e32 v109, 0xffff0000, v40
	v_lshlrev_b32_e32 v110, 16, v41
	v_and_b32_e32 v111, 0xffff0000, v41
	v_pk_mul_f32 v[108:109], v[204:205], v[108:109]
	v_pk_mul_f32 v[110:111], v[204:205], v[110:111]
	v_cvt_pk_bf16_f32 v108, v108, v109
	v_cvt_pk_bf16_f32 v109, v110, v111
	v_add_u32_e32 v110, v225, v228
	s_cmp_eq_u32 s31, 31
	ds_write_b128 v110, v[106:109]
	s_waitcnt lgkmcnt(0)
	s_barrier
	s_cbranch_scc1 .LBB0_413
; #define LAS __attribute__((address_space(3)))
; #define MFMA16(a, b, c) __builtin_amdgcn_mfma_f32_16x16x32_bf16((a), (b), (c), 0, 0, 0)
; __device__ __forceinline__ void ret_prompt_item(LAS unsigned char* lds, const bf16_t* z, bf16_t* o, float* state_out, int item, int tid) {
;     ...
;         if (c + 1 < 32) {
;             const size_t tk = tok0 + 128;
; #pragma unroll
;             for (int r = 0; r < 8; ++r) { const int idx = tid + 512 * r, row = idx >> 5, ch = idx & 31; kreg[r] = *(const u32x4*)(z + (tk + row) * RIN + 2048 + h * 256 + ch * 8); }
; #pragma unroll
;             for (int r = 0; r < 2; ++r) { const int idx = tid + 512 * r, row = idx >> 3, ch = idx & 7; vreg[r] = *(const u32x4*)(z + (tk + row) * RIN + 4096 + h * 512 + et * 64 + ch * 8); }
;         }
;         f32x4 ao[4];
; #pragma unroll
;         for (int e4 = 0; e4 < 4; ++e4) {
;             f32x4 a = {0.f, 0.f, 0.f, 0.f};
; #pragma unroll
;             for (int ks = 0; ks < 8; ++ks) { const bf16x8 sa = *(const LAS bf16x8*)(St + (16 * e4 + l15) * 528 + (32 * ks + 8 * g) * 2); a = MFMA16(sa, qf[ks], a); }
;             ao[e4] = a * qd;
;         }
	s_add_u32 s24, s24, 0x80
	s_addc_u32 s25, s25, 0
	s_mul_i32 s13, s24, 0x6000
	s_add_i32 s26, s13, s80
	s_addk_i32 s26, 0x1000
	s_add_u32 s26, s20, s26
	s_addc_u32 s27, s21, 0
	global_load_dwordx4 v[2:5], v162, s[26:27]
	s_add_u32 s26, s26, 0x60000
	s_addc_u32 s27, s27, 0
	global_load_dwordx4 v[6:9], v162, s[26:27]
	s_add_u32 s26, s26, 0x60000
	s_addc_u32 s27, s27, 0
	global_load_dwordx4 v[10:13], v162, s[26:27]
	s_add_u32 s26, s26, 0x60000
	s_addc_u32 s27, s27, 0
	global_load_dwordx4 v[14:17], v162, s[26:27]
	s_add_u32 s26, s26, 0x60000
	s_addc_u32 s27, s27, 0
	global_load_dwordx4 v[18:21], v162, s[26:27]
	s_add_u32 s26, s26, 0x60000
	s_addc_u32 s27, s27, 0
	global_load_dwordx4 v[22:25], v162, s[26:27]
	s_add_u32 s26, s26, 0x60000
	s_addc_u32 s27, s27, 0
	global_load_dwordx4 v[26:29], v162, s[26:27]
	s_add_u32 s26, s26, 0x60000
	s_addc_u32 s27, s27, 0
	global_load_dwordx4 v[30:33], v162, s[26:27]
	s_add_i32 s13, s13, s12
	s_lshl_b32 s26, s9, 1
	s_add_i32 s13, s13, s26
	s_addk_i32 s13, 0x2000
	s_add_u32 s26, s20, s13
	s_addc_u32 s27, s21, 0
	global_load_dwordx4 v[34:37], v163, s[26:27]
	s_add_u32 s26, s26, 0x180000
	s_addc_u32 s27, s27, 0
	global_load_dwordx4 v[38:41], v163, s[26:27]
	s_mov_b32 s13, 0
	v_mov_b32_e32 v187, v232
	v_sub_u32_e32 v191, v130, v166
	v_mov_b32_e32 v195, v231
	v_mov_b32_e32 v245, v166
	ds_read_b128 v[106:109], v241
	ds_read_b128 v[122:125], v241 offset:64
	ds_read_b128 v[126:129], v241 offset:128
	ds_read_b128 v[246:249], v241 offset:192
	ds_read_b128 v[250:253], v241 offset:256
	ds_read_b128 v[134:137], v241 offset:320
	ds_read_b128 v[146:149], v241 offset:384
	ds_read_b128 v[150:153], v241 offset:448
	ds_read_b128 v[110:113], v241 offset:8448
	s_waitcnt vmcnt(17) lgkmcnt(8)
	v_mfma_f32_16x16x32_bf16 v[106:109], v[106:109], v[74:77], 0
	ds_read_b128 v[154:157], v241 offset:8512
	s_waitcnt vmcnt(16) lgkmcnt(8)
	v_mfma_f32_16x16x32_bf16 v[106:109], v[122:125], v[78:81], v[106:109]
	ds_read_b128 v[122:125], v241 offset:8576
	s_waitcnt vmcnt(15) lgkmcnt(8)
	v_mfma_f32_16x16x32_bf16 v[106:109], v[126:129], v[82:85], v[106:109]
	ds_read_b128 v[126:129], v241 offset:8640
	s_waitcnt vmcnt(14) lgkmcnt(8)
	v_mfma_f32_16x16x32_bf16 v[106:109], v[246:249], v[86:89], v[106:109]
	ds_read_b128 v[246:249], v241 offset:8704
	s_waitcnt vmcnt(13) lgkmcnt(8)
	v_mfma_f32_16x16x32_bf16 v[106:109], v[250:253], v[90:93], v[106:109]
	ds_read_b128 v[250:253], v241 offset:8768
	s_waitcnt vmcnt(12) lgkmcnt(8)
	v_mfma_f32_16x16x32_bf16 v[106:109], v[134:137], v[94:97], v[106:109]
	ds_read_b128 v[134:137], v241 offset:8832
	s_waitcnt vmcnt(11) lgkmcnt(8)
	v_mfma_f32_16x16x32_bf16 v[106:109], v[146:149], v[98:101], v[106:109]
	ds_read_b128 v[146:149], v241 offset:8896
	s_waitcnt vmcnt(10) lgkmcnt(8)
	v_mfma_f32_16x16x32_bf16 v[106:109], v[150:153], v[102:105], v[106:109]
	ds_read_b128 v[114:117], v241 offset:16896
	s_waitcnt lgkmcnt(8)
	v_mfma_f32_16x16x32_bf16 v[110:113], v[110:113], v[74:77], 0
	ds_read_b128 v[150:153], v241 offset:16960
	s_waitcnt lgkmcnt(8)
	v_mfma_f32_16x16x32_bf16 v[110:113], v[154:157], v[78:81], v[110:113]
	ds_read_b128 v[154:157], v241 offset:17024
	s_waitcnt lgkmcnt(8)
	v_mfma_f32_16x16x32_bf16 v[110:113], v[122:125], v[82:85], v[110:113]
	ds_read_b128 v[122:125], v241 offset:17088
	s_waitcnt lgkmcnt(8)
	v_mfma_f32_16x16x32_bf16 v[110:113], v[126:129], v[86:89], v[110:113]
	ds_read_b128 v[126:129], v241 offset:17152
	s_waitcnt lgkmcnt(8)
	v_mfma_f32_16x16x32_bf16 v[110:113], v[246:249], v[90:93], v[110:113]
	ds_read_b128 v[246:249], v241 offset:17216
	s_waitcnt lgkmcnt(8)
	v_mfma_f32_16x16x32_bf16 v[110:113], v[250:253], v[94:97], v[110:113]
	v_pk_mul_f32 v[108:109], v[198:199], v[108:109]
	v_mul_f32_e64 v106, v192, v106
	v_mul_f32_e64 v107, v193, v107
	ds_read_b128 v[250:253], v241 offset:17280
	s_waitcnt lgkmcnt(8)
	v_mfma_f32_16x16x32_bf16 v[110:113], v[134:137], v[98:101], v[110:113]
	ds_read_b128 v[134:137], v241 offset:17344
	s_waitcnt lgkmcnt(8)
	v_mfma_f32_16x16x32_bf16 v[110:113], v[146:149], v[102:105], v[110:113]
	ds_read_b128 v[118:121], v241 offset:25344
	s_waitcnt lgkmcnt(8)
	v_mfma_f32_16x16x32_bf16 v[114:117], v[114:117], v[74:77], 0
	ds_read_b128 v[146:149], v241 offset:25408
	s_waitcnt lgkmcnt(8)
	v_mfma_f32_16x16x32_bf16 v[114:117], v[150:153], v[78:81], v[114:117]
	ds_read_b128 v[150:153], v241 offset:25472
	s_waitcnt lgkmcnt(8)
	v_mfma_f32_16x16x32_bf16 v[114:117], v[154:157], v[82:85], v[114:117]
	ds_read_b128 v[154:157], v241 offset:25536
	s_waitcnt lgkmcnt(8)
	v_mfma_f32_16x16x32_bf16 v[114:117], v[122:125], v[86:89], v[114:117]
	ds_read_b128 v[122:125], v241 offset:25600
	s_waitcnt lgkmcnt(8)
	v_mfma_f32_16x16x32_bf16 v[114:117], v[126:129], v[90:93], v[114:117]
	ds_read_b128 v[126:129], v241 offset:25664
	s_waitcnt lgkmcnt(8)
	v_mfma_f32_16x16x32_bf16 v[114:117], v[246:249], v[94:97], v[114:117]
	v_pk_mul_f32 v[112:113], v[198:199], v[112:113]
	v_mul_f32_e64 v110, v192, v110
	v_mul_f32_e64 v111, v193, v111
	ds_read_b128 v[246:249], v241 offset:25728
	s_waitcnt lgkmcnt(8)
	v_mfma_f32_16x16x32_bf16 v[114:117], v[250:253], v[98:101], v[114:117]
	ds_read_b128 v[250:253], v241 offset:25792
	s_waitcnt lgkmcnt(8)
	v_mfma_f32_16x16x32_bf16 v[114:117], v[134:137], v[102:105], v[114:117]
	s_waitcnt lgkmcnt(7)
	v_mfma_f32_16x16x32_bf16 v[118:121], v[118:121], v[74:77], 0
	s_waitcnt lgkmcnt(6)
	v_mfma_f32_16x16x32_bf16 v[118:121], v[146:149], v[78:81], v[118:121]
	s_waitcnt lgkmcnt(5)
	v_mfma_f32_16x16x32_bf16 v[118:121], v[150:153], v[82:85], v[118:121]
	s_waitcnt lgkmcnt(4)
	v_mfma_f32_16x16x32_bf16 v[118:121], v[154:157], v[86:89], v[118:121]
	s_waitcnt lgkmcnt(3)
	v_mfma_f32_16x16x32_bf16 v[118:121], v[122:125], v[90:93], v[118:121]
	s_waitcnt lgkmcnt(2)
	v_mfma_f32_16x16x32_bf16 v[118:121], v[126:129], v[94:97], v[118:121]
	v_pk_mul_f32 v[116:117], v[198:199], v[116:117]
	v_mul_f32_e64 v114, v192, v114
	v_mul_f32_e64 v115, v193, v115
	s_waitcnt lgkmcnt(1)
	v_mfma_f32_16x16x32_bf16 v[118:121], v[246:249], v[98:101], v[118:121]
	s_waitcnt lgkmcnt(0)
	v_mfma_f32_16x16x32_bf16 v[118:121], v[250:253], v[102:105], v[118:121]
	s_nop 7
	v_pk_mul_f32 v[120:121], v[198:199], v[120:121]
	v_pk_mul_f32 v[118:119], v[192:193], v[118:119]
	s_branch .LBB0_416
; #define LAS __attribute__((address_space(3)))
; #define MFMA16(a, b, c) __builtin_amdgcn_mfma_f32_16x16x32_bf16((a), (b), (c), 0, 0, 0)
; __device__ __forceinline__ void ret_prompt_item(LAS unsigned char* lds, const bf16_t* z, bf16_t* o, float* state_out, int item, int tid) {
;     ...
;         f32x4 ao[4];
; #pragma unroll
;         for (int e4 = 0; e4 < 4; ++e4) {
;             f32x4 a = {0.f, 0.f, 0.f, 0.f};
; #pragma unroll
;             for (int ks = 0; ks < 8; ++ks) { const bf16x8 sa = *(const LAS bf16x8*)(St + (16 * e4 + l15) * 528 + (32 * ks + 8 * g) * 2); a = MFMA16(sa, qf[ks], a); }
;             ao[e4] = a * qd;
;         }
.LBB0_413:
	s_mov_b32 s13, 0
	v_mov_b32_e32 v187, v232
	v_sub_u32_e32 v191, v130, v166
	v_mov_b32_e32 v195, v231
	v_mov_b32_e32 v245, v166
	ds_read_b128 v[106:109], v241
	ds_read_b128 v[122:125], v241 offset:64
	ds_read_b128 v[126:129], v241 offset:128
	ds_read_b128 v[246:249], v241 offset:192
	ds_read_b128 v[250:253], v241 offset:256
	ds_read_b128 v[134:137], v241 offset:320
	ds_read_b128 v[146:149], v241 offset:384
	ds_read_b128 v[150:153], v241 offset:448
	ds_read_b128 v[110:113], v241 offset:8448
	s_waitcnt vmcnt(7) lgkmcnt(8)
	v_mfma_f32_16x16x32_bf16 v[106:109], v[106:109], v[74:77], 0
	ds_read_b128 v[154:157], v241 offset:8512
	s_waitcnt vmcnt(6) lgkmcnt(8)
	v_mfma_f32_16x16x32_bf16 v[106:109], v[122:125], v[78:81], v[106:109]
	ds_read_b128 v[122:125], v241 offset:8576
	s_waitcnt vmcnt(5) lgkmcnt(8)
	v_mfma_f32_16x16x32_bf16 v[106:109], v[126:129], v[82:85], v[106:109]
	ds_read_b128 v[126:129], v241 offset:8640
	s_waitcnt vmcnt(4) lgkmcnt(8)
	v_mfma_f32_16x16x32_bf16 v[106:109], v[246:249], v[86:89], v[106:109]
	ds_read_b128 v[246:249], v241 offset:8704
	s_waitcnt vmcnt(3) lgkmcnt(8)
	v_mfma_f32_16x16x32_bf16 v[106:109], v[250:253], v[90:93], v[106:109]
	ds_read_b128 v[250:253], v241 offset:8768
	s_waitcnt vmcnt(2) lgkmcnt(8)
	v_mfma_f32_16x16x32_bf16 v[106:109], v[134:137], v[94:97], v[106:109]
	ds_read_b128 v[134:137], v241 offset:8832
	s_waitcnt vmcnt(1) lgkmcnt(8)
	v_mfma_f32_16x16x32_bf16 v[106:109], v[146:149], v[98:101], v[106:109]
	ds_read_b128 v[146:149], v241 offset:8896
	s_waitcnt vmcnt(0) lgkmcnt(8)
	v_mfma_f32_16x16x32_bf16 v[106:109], v[150:153], v[102:105], v[106:109]
	ds_read_b128 v[114:117], v241 offset:16896
	s_waitcnt lgkmcnt(8)
	v_mfma_f32_16x16x32_bf16 v[110:113], v[110:113], v[74:77], 0
	ds_read_b128 v[150:153], v241 offset:16960
	s_waitcnt lgkmcnt(8)
	v_mfma_f32_16x16x32_bf16 v[110:113], v[154:157], v[78:81], v[110:113]
	ds_read_b128 v[154:157], v241 offset:17024
	s_waitcnt lgkmcnt(8)
	v_mfma_f32_16x16x32_bf16 v[110:113], v[122:125], v[82:85], v[110:113]
	ds_read_b128 v[122:125], v241 offset:17088
	s_waitcnt lgkmcnt(8)
	v_mfma_f32_16x16x32_bf16 v[110:113], v[126:129], v[86:89], v[110:113]
	ds_read_b128 v[126:129], v241 offset:17152
	s_waitcnt lgkmcnt(8)
	v_mfma_f32_16x16x32_bf16 v[110:113], v[246:249], v[90:93], v[110:113]
	ds_read_b128 v[246:249], v241 offset:17216
	s_waitcnt lgkmcnt(8)
	v_mfma_f32_16x16x32_bf16 v[110:113], v[250:253], v[94:97], v[110:113]
	v_pk_mul_f32 v[108:109], v[198:199], v[108:109]
	v_mul_f32_e64 v106, v192, v106
	v_mul_f32_e64 v107, v193, v107
	ds_read_b128 v[250:253], v241 offset:17280
	s_waitcnt lgkmcnt(8)
	v_mfma_f32_16x16x32_bf16 v[110:113], v[134:137], v[98:101], v[110:113]
	ds_read_b128 v[134:137], v241 offset:17344
	s_waitcnt lgkmcnt(8)
	v_mfma_f32_16x16x32_bf16 v[110:113], v[146:149], v[102:105], v[110:113]
	ds_read_b128 v[118:121], v241 offset:25344
	s_waitcnt lgkmcnt(8)
	v_mfma_f32_16x16x32_bf16 v[114:117], v[114:117], v[74:77], 0
	ds_read_b128 v[146:149], v241 offset:25408
	s_waitcnt lgkmcnt(8)
	v_mfma_f32_16x16x32_bf16 v[114:117], v[150:153], v[78:81], v[114:117]
	ds_read_b128 v[150:153], v241 offset:25472
	s_waitcnt lgkmcnt(8)
	v_mfma_f32_16x16x32_bf16 v[114:117], v[154:157], v[82:85], v[114:117]
	ds_read_b128 v[154:157], v241 offset:25536
	s_waitcnt lgkmcnt(8)
	v_mfma_f32_16x16x32_bf16 v[114:117], v[122:125], v[86:89], v[114:117]
	ds_read_b128 v[122:125], v241 offset:25600
	s_waitcnt lgkmcnt(8)
	v_mfma_f32_16x16x32_bf16 v[114:117], v[126:129], v[90:93], v[114:117]
	ds_read_b128 v[126:129], v241 offset:25664
	s_waitcnt lgkmcnt(8)
	v_mfma_f32_16x16x32_bf16 v[114:117], v[246:249], v[94:97], v[114:117]
	v_pk_mul_f32 v[112:113], v[198:199], v[112:113]
	v_mul_f32_e64 v110, v192, v110
	v_mul_f32_e64 v111, v193, v111
	ds_read_b128 v[246:249], v241 offset:25728
	s_waitcnt lgkmcnt(8)
	v_mfma_f32_16x16x32_bf16 v[114:117], v[250:253], v[98:101], v[114:117]
	ds_read_b128 v[250:253], v241 offset:25792
	s_waitcnt lgkmcnt(8)
	v_mfma_f32_16x16x32_bf16 v[114:117], v[134:137], v[102:105], v[114:117]
	s_waitcnt lgkmcnt(7)
	v_mfma_f32_16x16x32_bf16 v[118:121], v[118:121], v[74:77], 0
	s_waitcnt lgkmcnt(6)
	v_mfma_f32_16x16x32_bf16 v[118:121], v[146:149], v[78:81], v[118:121]
	s_waitcnt lgkmcnt(5)
	v_mfma_f32_16x16x32_bf16 v[118:121], v[150:153], v[82:85], v[118:121]
	s_waitcnt lgkmcnt(4)
	v_mfma_f32_16x16x32_bf16 v[118:121], v[154:157], v[86:89], v[118:121]
	s_waitcnt lgkmcnt(3)
	v_mfma_f32_16x16x32_bf16 v[118:121], v[122:125], v[90:93], v[118:121]
	s_waitcnt lgkmcnt(2)
	v_mfma_f32_16x16x32_bf16 v[118:121], v[126:129], v[94:97], v[118:121]
	v_pk_mul_f32 v[116:117], v[198:199], v[116:117]
	v_mul_f32_e64 v114, v192, v114
	v_mul_f32_e64 v115, v193, v115
	s_waitcnt lgkmcnt(1)
	v_mfma_f32_16x16x32_bf16 v[118:121], v[246:249], v[98:101], v[118:121]
	s_waitcnt lgkmcnt(0)
	v_mfma_f32_16x16x32_bf16 v[118:121], v[250:253], v[102:105], v[118:121]
	s_nop 7
	v_pk_mul_f32 v[120:121], v[198:199], v[120:121]
	v_pk_mul_f32 v[118:119], v[192:193], v[118:119]
	s_branch .LBB0_416
; #define LAS __attribute__((address_space(3)))
; #define MFMA16(a, b, c) __builtin_amdgcn_mfma_f32_16x16x32_bf16((a), (b), (c), 0, 0, 0)
; __device__ __forceinline__ unsigned pk2(float lo, float hi) { return pg8::cvt_pk_bf16(lo, hi); }
; __device__ __forceinline__ void ret_prompt_item(LAS unsigned char* lds, const bf16_t* z, bf16_t* o, float* state_out, int item, int tid) {
;     ...
;                 float d0[4], d1[4];
; #pragma unroll
;                 for (int jj = 0; jj < 4; ++jj) {
;                     const int j0 = 32 * u + 4 * g + jj, j1 = j0 + 16;
;                     d0[jj] = (i >= j0) ? p0[jj] * __builtin_amdgcn_exp2f((float)(i - j0) * lg2) : 0.f;
;                     d1[jj] = (i >= j1) ? p1[jj] * __builtin_amdgcn_exp2f((float)(i - j1) * lg2) : 0.f;
;                 }
;                 u32x4 pw; pw.x = pk2(d0[0], d0[1]); pw.y = pk2(d0[2], d0[3]); pw.z = pk2(d1[0], d1[1]); pw.w = pk2(d1[2], d1[3]);
;                 const bf16x8 pb = as_bf16x8(pw);
; #pragma unroll
;                 for (int e4 = 0; e4 < 4; ++e4) {
;                     LAS unsigned char* ap = Vn + (32 * u + 4 * g + q4) * 144 + (16 * e4 + 4 * p4) * 2;
;                     const bf16x8 va = tr_read8(ap, ap + 16 * 144);
;                     ao[e4] = MFMA16(va, pb, ao[e4]);
;                 }
.LBB0_414:
	s_or_b64 exec, exec, s[26:27]
	v_cvt_f32_i32_e32 v246, v191
	v_cmp_ge_i32_e32 vcc, v130, v245
	v_or_b32_e32 v248, 17, v245
	v_or_b32_e32 v249, 16, v245
	v_mul_f32_e32 v246, v189, v246
	v_exp_f32_e32 v246, v246
	v_or_b32_e32 v250, 3, v245
	v_or_b32_e32 v251, 2, v245
	v_or_b32_e32 v252, 19, v245
	v_mul_f32_e32 v122, v246, v122
	v_cndmask_b32_e32 v246, 0, v122, vcc
	v_add_u32_e32 v122, -1, v191
	v_cvt_f32_i32_e32 v122, v122
	v_cmp_gt_i32_e32 vcc, v130, v245
	v_or_b32_e32 v253, 18, v245
	v_mul_f32_e32 v122, v189, v122
	v_exp_f32_e32 v122, v122
	s_nop 0
	v_mul_f32_e32 v122, v122, v123
	v_cndmask_b32_e32 v247, 0, v122, vcc
	v_sub_u32_e32 v122, v130, v249
	v_sub_u32_e32 v123, v130, v248
	v_cvt_f32_i32_e32 v122, v122
	v_cvt_f32_i32_e32 v123, v123
	v_cmp_ge_i32_e32 vcc, v184, v251
	v_mul_f32_e32 v122, v189, v122
	v_mul_f32_e32 v123, v189, v123
	v_exp_f32_e32 v122, v122
	v_exp_f32_e32 v123, v123
	s_nop 0
	v_pk_mul_f32 v[126:127], v[122:123], v[126:127]
	v_sub_u32_e32 v122, v130, v251
	v_sub_u32_e32 v123, v130, v250
	v_cvt_f32_i32_e32 v122, v122
	v_cvt_f32_i32_e32 v123, v123
	v_mul_f32_e32 v122, v189, v122
	v_mul_f32_e32 v123, v189, v123
	v_exp_f32_e32 v122, v122
	v_exp_f32_e32 v123, v123
	s_nop 0
	v_pk_mul_f32 v[124:125], v[122:123], v[124:125]
	v_sub_u32_e32 v122, v130, v253
	v_sub_u32_e32 v123, v130, v252
	v_cvt_f32_i32_e32 v122, v122
	v_cvt_f32_i32_e32 v123, v123
	v_mul_f32_e32 v122, v189, v122
	v_mul_f32_e32 v123, v189, v123
	v_exp_f32_e32 v122, v122
	v_exp_f32_e32 v123, v123
	s_nop 0
	v_pk_mul_f32 v[128:129], v[122:123], v[128:129]
	v_cvt_pk_bf16_f32 v123, v124, v125
	v_cndmask_b32_e32 v124, 0, v123, vcc
	v_lshrrev_b32_e32 v123, 16, v123
	v_cmp_ge_i32_e32 vcc, v133, v250
	v_cvt_pk_bf16_f32 v122, v246, v247
	v_add_u32_e32 v246, 0, v195
	v_cndmask_b32_e32 v123, 0, v123, vcc
	v_perm_b32 v123, v123, v124, s66
	v_cvt_pk_bf16_f32 v124, v126, v127
	v_cmp_ge_i32_e32 vcc, v184, v249
	s_nop 1
	v_cndmask_b32_e32 v125, 0, v124, vcc
	v_lshrrev_b32_e32 v124, 16, v124
	v_cmp_ge_i32_e32 vcc, v133, v248
	s_nop 1
	v_cndmask_b32_e32 v124, 0, v124, vcc
	v_perm_b32 v124, v124, v125, s66
	v_cvt_pk_bf16_f32 v125, v128, v129
	v_cmp_ge_i32_e32 vcc, v184, v253
	v_add_u32_e32 v128, 0x11100, v246
	s_nop 0
	v_cndmask_b32_e32 v126, 0, v125, vcc
	v_lshrrev_b32_e32 v125, 16, v125
	v_cmp_ge_i32_e32 vcc, v133, v252
	s_nop 1
	v_cndmask_b32_e32 v125, 0, v125, vcc
	v_perm_b32 v125, v125, v126, s66
	v_add_u32_e32 v126, 0x10800, v246
	ds_read_b64_tr_b16 v[246:247], v126
	ds_read_b64_tr_b16 v[248:249], v126 offset:2304
	ds_read_b64_tr_b16 v[250:251], v126 offset:32
	ds_read_b64_tr_b16 v[252:253], v126 offset:2336
	ds_read_b64_tr_b16 v[134:135], v126 offset:64
	ds_read_b64_tr_b16 v[136:137], v126 offset:2368
	ds_read_b64_tr_b16 v[146:147], v126 offset:96
	ds_read_b64_tr_b16 v[148:149], v126 offset:2400
	s_waitcnt lgkmcnt(6)
	v_mfma_f32_16x16x32_bf16 v[106:109], v[246:249], v[122:125], v[106:109]
	s_waitcnt lgkmcnt(4)
	v_mfma_f32_16x16x32_bf16 v[110:113], v[250:253], v[122:125], v[110:113]
	s_waitcnt lgkmcnt(2)
	v_mfma_f32_16x16x32_bf16 v[114:117], v[134:137], v[122:125], v[114:117]
	s_waitcnt lgkmcnt(0)
	v_mfma_f32_16x16x32_bf16 v[118:121], v[146:149], v[122:125], v[118:121]

; #define LAS __attribute__((address_space(3)))
; #define MFMA16(a, b, c) __builtin_amdgcn_mfma_f32_16x16x32_bf16((a), (b), (c), 0, 0, 0)
; __device__ __forceinline__ void ret_prompt_item(LAS unsigned char* lds, const bf16_t* z, bf16_t* o, float* state_out, int item, int tid) {
;     ...
;         for (int u = 0; u < 4; ++u) {
;             if (2 * u <= itw) {
;                 f32x4 p0 = {0.f, 0.f, 0.f, 0.f}, p1 = {0.f, 0.f, 0.f, 0.f};
; #pragma unroll
;                 for (int ks = 0; ks < 8; ++ks) { const bf16x8 ka = *(const LAS bf16x8*)(Kn + (32 * u + l15) * 528 + (32 * ks + 8 * g) * 2); p0 = MFMA16(ka, qf[ks], p0); }
;                 if (2 * u + 1 <= itw) {
; #pragma unroll
;                     for (int ks = 0; ks < 8; ++ks) { const bf16x8 ka = *(const LAS bf16x8*)(Kn + (32 * u + 16 + l15) * 528 + (32 * ks + 8 * g) * 2); p1 = MFMA16(ka, qf[ks], p1); }
;                 }
.LBB0_416:
	v_cmp_le_i32_e32 vcc, s13, v159
	s_and_saveexec_b64 s[24:25], vcc
	s_cbranch_execz .LBB0_415
	v_cmp_lt_i32_e32 vcc, s13, v159
	ds_read_b128 v[122:125], v187
	ds_read_b128 v[126:129], v187 offset:64
	ds_read_b128 v[246:249], v187 offset:128
	ds_read_b128 v[250:253], v187 offset:192
	ds_read_b128 v[134:137], v187 offset:256
	ds_read_b128 v[146:149], v187 offset:320
	ds_read_b128 v[150:153], v187 offset:384
	ds_read_b128 v[154:157], v187 offset:448
	s_waitcnt lgkmcnt(7)
	v_mfma_f32_16x16x32_bf16 v[122:125], v[122:125], v[74:77], 0
	s_waitcnt lgkmcnt(6)
	v_mfma_f32_16x16x32_bf16 v[122:125], v[126:129], v[78:81], v[122:125]
	s_waitcnt lgkmcnt(5)
	v_mfma_f32_16x16x32_bf16 v[122:125], v[246:249], v[82:85], v[122:125]
	s_waitcnt lgkmcnt(4)
	v_mfma_f32_16x16x32_bf16 v[122:125], v[250:253], v[86:89], v[122:125]
	s_waitcnt lgkmcnt(3)
	v_mfma_f32_16x16x32_bf16 v[122:125], v[134:137], v[90:93], v[122:125]
	s_waitcnt lgkmcnt(2)
	v_mfma_f32_16x16x32_bf16 v[122:125], v[146:149], v[94:97], v[122:125]
	s_waitcnt lgkmcnt(1)
	v_mfma_f32_16x16x32_bf16 v[122:125], v[150:153], v[98:101], v[122:125]
	s_waitcnt lgkmcnt(0)
	v_mfma_f32_16x16x32_bf16 v[122:125], v[154:157], v[102:105], v[122:125]
	v_mov_b32_e32 v126, 0
	v_mov_b32_e32 v127, 0
	v_mov_b32_e32 v128, 0
	v_mov_b32_e32 v129, 0
	s_and_saveexec_b64 s[26:27], vcc
	s_cbranch_execz .LBB0_414
	ds_read_b128 v[126:129], v187 offset:8448
	ds_read_b128 v[246:249], v187 offset:8512
	ds_read_b128 v[250:253], v187 offset:8576
	ds_read_b128 v[134:137], v187 offset:8640
	ds_read_b128 v[146:149], v187 offset:8704
	ds_read_b128 v[150:153], v187 offset:8768
	ds_read_b128 v[154:157], v187 offset:8832
	s_waitcnt lgkmcnt(6)
	v_mfma_f32_16x16x32_bf16 v[126:129], v[126:129], v[74:77], 0
	s_waitcnt lgkmcnt(5)
	v_mfma_f32_16x16x32_bf16 v[126:129], v[246:249], v[78:81], v[126:129]
	ds_read_b128 v[246:249], v187 offset:8896
	s_waitcnt lgkmcnt(5)
	v_mfma_f32_16x16x32_bf16 v[126:129], v[250:253], v[82:85], v[126:129]
	s_waitcnt lgkmcnt(4)
	v_mfma_f32_16x16x32_bf16 v[126:129], v[134:137], v[86:89], v[126:129]
	s_waitcnt lgkmcnt(3)
	v_mfma_f32_16x16x32_bf16 v[126:129], v[146:149], v[90:93], v[126:129]
	s_waitcnt lgkmcnt(2)
	v_mfma_f32_16x16x32_bf16 v[126:129], v[150:153], v[94:97], v[126:129]
	s_waitcnt lgkmcnt(1)
	v_mfma_f32_16x16x32_bf16 v[126:129], v[154:157], v[98:101], v[126:129]
	s_waitcnt lgkmcnt(0)
	v_mfma_f32_16x16x32_bf16 v[126:129], v[246:249], v[102:105], v[126:129]
	s_branch .LBB0_414

; #define MFMA16(a, b, c) __builtin_amdgcn_mfma_f32_16x16x32_bf16((a), (b), (c), 0, 0, 0)
; __device__ __forceinline__ float bf_lo(unsigned w) { return __uint_as_float(w << 16); }
; __device__ __forceinline__ float bf_hi(unsigned w) { return __uint_as_float(w & 0xffff0000u); }
; __device__ __forceinline__ unsigned pk2(float lo, float hi) { return pg8::cvt_pk_bf16(lo, hi); }
; __device__ __forceinline__ void xattn_prompt_item(const bf16_t* xq, const bf16_t* xq1, const bf16_t* memkv, const bf16_t* memvt, bf16_t* xo, int l, int it, int lane) {
;     const int h = it & 3, qt = it >> 2, b = qt >> 8;
;     const int l15 = lane & 15, g = lane >> 4;
;     const size_t tok = (size_t)qt * 16 + l15;
;     bf16x8 qf[4];
; #pragma unroll
;     for (int ks = 0; ks < 4; ++ks) {
;         const u32x4 a = *(const u32x4*)(xq + tok * 512 + h * 128 + 32 * ks + 8 * g), c = *(const u32x4*)(xq1 + tok * 512 + h * 128 + 32 * ks + 8 * g);
;         u32x4 w; w.x = pk2(bf_lo(a.x) + bf_lo(c.x), bf_hi(a.x) + bf_hi(c.x)); w.y = pk2(bf_lo(a.y) + bf_lo(c.y), bf_hi(a.y) + bf_hi(c.y));
;         w.z = pk2(bf_lo(a.z) + bf_lo(c.z), bf_hi(a.z) + bf_hi(c.z)); w.w = pk2(bf_lo(a.w) + bf_lo(c.w), bf_hi(a.w) + bf_hi(c.w));
;         qf[ks] = as_bf16x8(w);
;     }
;     f32x4 sc[16];
;     float mx = -1e30f;
; #pragma unroll
;     for (int kt = 0; kt < 16; ++kt) {
;         const bf16_t* kp = memkv + ((size_t)b * 256 + 16 * kt + l15) * 4096 + l * 1024 + h * 128 + 8 * g;
;         f32x4 a = {0.f, 0.f, 0.f, 0.f};
; #pragma unroll
;         for (int ks = 0; ks < 4; ++ks) a = MFMA16(*(const bf16x8*)(kp + 32 * ks), qf[ks], a);
.LBB0_1402:
	s_mov_b32 s6, s26
	s_movk_i32 s7, 0xff
	s_cmpk_eq_i32 s88, 0x100
	s_cselect_b32 s7, 0x7f, s7
	s_cmp_gt_i32 s6, s7
	s_cbranch_scc1 .LBB0_1405
	v_lshrrev_b32_e32 v8, 4, v139
	v_and_b32_e32 v9, 15, v139
	v_lshlrev_b32_e32 v9, 4, v9
	v_lshl_add_u32 v58, v8, 13, v9
	v_bfe_u32 v0, v8, 2, 1
	v_lshlrev_b32_e32 v0, 4, v0
	v_lshrrev_b32_e32 v136, 3, v8
	v_lshl_add_u32 v0, v136, 2, v0
	v_and_b32_e32 v136, 3, v8
	v_add_u32_e32 v0, v0, v136
	v_mul_u32_u24_e32 v0, 272, v0
	v_add_u32_e32 v59, v0, v9
	v_lshrrev_b32_e32 v8, 5, v139
	v_and_b32_e32 v9, 31, v139
	v_lshlrev_b32_e32 v9, 4, v9
	v_lshl_add_u32 v60, v8, 9, v9
	v_mul_u32_u24_e32 v0, 528, v8
	v_add_u32_e32 v61, v0, v9
	v_add_u32_e32 v61, 0x11000, v61
	v_and_b32_e32 v0, 15, v215
	v_lshrrev_b32_e32 v8, 4, v215
	v_lshlrev_b32_e32 v9, 4, v8
	v_lshl_add_u32 v2, v0, 10, v9
	v_lshlrev_b32_e32 v5, 3, v8
	v_lshl_add_u32 v5, v0, 10, v5
	v_mul_u32_u24_e32 v3, 272, v0
	v_add_u32_e32 v3, v3, v9
	v_mul_u32_u24_e32 v4, 528, v0
	v_add_u32_e32 v4, v4, v9
	v_add_u32_e32 v4, 0x11000, v4
	v_xor_b32_e32 v6, 16, v215
	v_lshlrev_b32_e32 v6, 2, v6
	v_xor_b32_e32 v7, 32, v215
	v_lshlrev_b32_e32 v7, 2, v7
.Lxp_pair:
	s_and_b32 s7, s6, 3
	s_lshr_b32 s4, s6, 2
	s_lshr_b32 s5, s4, 5
	s_lshl_b32 s4, s4, 3
	s_ashr_i32 s16, s27, 6
	s_add_i32 s4, s4, s16
	s_lshl_b32 s80, s7, 8
	s_lshl_b32 s4, s4, 14
	s_add_i32 s4, s4, s80
	s_add_u32 s22, s10, s4
	s_addc_u32 s23, s11, 0
	s_add_u32 s24, s12, s4
	s_addc_u32 s25, s13, 0
	global_load_dwordx4 v[26:29], v2, s[22:23] offset:0
	global_load_dwordx4 v[30:33], v2, s[22:23] offset:64
	global_load_dwordx4 v[34:37], v2, s[22:23] offset:128
	global_load_dwordx4 v[38:41], v2, s[22:23] offset:192
	global_load_dwordx4 v[42:45], v2, s[24:25] offset:0
	global_load_dwordx4 v[46:49], v2, s[24:25] offset:64
	global_load_dwordx4 v[50:53], v2, s[24:25] offset:128
	global_load_dwordx4 v[54:57], v2, s[24:25] offset:192
	v_readlane_b32 s18, v254, 42
	v_readlane_b32 s19, v254, 43
	v_readlane_b32 s20, v254, 38
	s_nop 0
	s_lshl_b32 s21, s20, 11
	s_add_i32 s21, s21, s80
	s_lshl_b32 s16, s5, 21
	s_add_i32 s21, s21, s16
	s_add_u32 s16, s18, 0x28c28000
	s_addc_u32 s17, s19, 0
	s_add_u32 s16, s16, s21
	s_addc_u32 s17, s17, 0
	s_lshl_b32 s20, s20, 1
	s_add_i32 s20, s20, s5
	s_lshl_b32 s20, s20, 18
	s_lshl_b32 s21, s7, 16
	s_add_i32 s21, s21, s20
	s_add_u32 s20, s18, 0x29028000
	s_addc_u32 s19, s19, 0
	s_add_u32 s20, s20, s21
	s_addc_u32 s21, s19, 0
	s_add_u32 s4, s14, s4
	s_addc_u32 s5, s15, 0
	global_load_dwordx4 v[146:149], v58, s[16:17]
	s_add_u32 s16, s16, 0x40000
	s_addc_u32 s17, s17, 0
	global_load_dwordx4 v[150:153], v58, s[16:17]
	s_add_u32 s16, s16, 0x40000
	s_addc_u32 s17, s17, 0
	global_load_dwordx4 v[154:157], v58, s[16:17]
	s_add_u32 s16, s16, 0x40000
	s_addc_u32 s17, s17, 0
	global_load_dwordx4 v[158:161], v58, s[16:17]
	s_add_u32 s16, s16, 0x40000
	s_addc_u32 s17, s17, 0
	global_load_dwordx4 v[162:165], v58, s[16:17]
	s_add_u32 s16, s16, 0x40000
	s_addc_u32 s17, s17, 0
	global_load_dwordx4 v[166:169], v58, s[16:17]
	s_add_u32 s16, s16, 0x40000
	s_addc_u32 s17, s17, 0
	global_load_dwordx4 v[170:173], v58, s[16:17]
	s_add_u32 s16, s16, 0x40000
	s_addc_u32 s17, s17, 0
	global_load_dwordx4 v[174:177], v58, s[16:17]
	global_load_dwordx4 v[178:181], v60, s[20:21]
	s_add_u32 s20, s20, 0x2000
	s_addc_u32 s21, s21, 0
	global_load_dwordx4 v[182:185], v60, s[20:21]
	s_add_u32 s20, s20, 0x2000
	s_addc_u32 s21, s21, 0
	global_load_dwordx4 v[186:189], v60, s[20:21]
	s_add_u32 s20, s20, 0x2000
	s_addc_u32 s21, s21, 0
	global_load_dwordx4 v[190:193], v60, s[20:21]
	s_add_u32 s20, s20, 0x2000
	s_addc_u32 s21, s21, 0
	global_load_dwordx4 v[194:197], v60, s[20:21]
	s_add_u32 s20, s20, 0x2000
	s_addc_u32 s21, s21, 0
	global_load_dwordx4 v[198:201], v60, s[20:21]
	s_add_u32 s20, s20, 0x2000
	s_addc_u32 s21, s21, 0
	global_load_dwordx4 v[202:205], v60, s[20:21]
	s_add_u32 s20, s20, 0x2000
	s_addc_u32 s21, s21, 0
	global_load_dwordx4 v[206:209], v60, s[20:21]
	s_waitcnt vmcnt(16)
	v_lshlrev_b32_e32 v8, 16, v26
	v_and_b32_e32 v9, 0xffff0000, v26
	v_lshlrev_b32_e32 v136, 16, v42
	v_and_b32_e32 v137, 0xffff0000, v42
	v_pk_add_f32 v[8:9], v[8:9], v[136:137]
	v_cvt_pk_bf16_f32 v10, v8, v9
	v_lshlrev_b32_e32 v8, 16, v27
	v_and_b32_e32 v9, 0xffff0000, v27
	v_lshlrev_b32_e32 v136, 16, v43
	v_and_b32_e32 v137, 0xffff0000, v43
	v_pk_add_f32 v[8:9], v[8:9], v[136:137]
	v_cvt_pk_bf16_f32 v11, v8, v9
	v_lshlrev_b32_e32 v8, 16, v28
	v_and_b32_e32 v9, 0xffff0000, v28
	v_lshlrev_b32_e32 v136, 16, v44
	v_and_b32_e32 v137, 0xffff0000, v44
	v_pk_add_f32 v[8:9], v[8:9], v[136:137]
	v_cvt_pk_bf16_f32 v12, v8, v9
	v_lshlrev_b32_e32 v8, 16, v29
	v_and_b32_e32 v9, 0xffff0000, v29
	v_lshlrev_b32_e32 v136, 16, v45
	v_and_b32_e32 v137, 0xffff0000, v45
	v_pk_add_f32 v[8:9], v[8:9], v[136:137]
	v_cvt_pk_bf16_f32 v13, v8, v9
	v_lshlrev_b32_e32 v8, 16, v30
	v_and_b32_e32 v9, 0xffff0000, v30
	v_lshlrev_b32_e32 v136, 16, v46
	v_and_b32_e32 v137, 0xffff0000, v46
	v_pk_add_f32 v[8:9], v[8:9], v[136:137]
	v_cvt_pk_bf16_f32 v14, v8, v9
	v_lshlrev_b32_e32 v8, 16, v31
	v_and_b32_e32 v9, 0xffff0000, v31
	v_lshlrev_b32_e32 v136, 16, v47
	v_and_b32_e32 v137, 0xffff0000, v47
	v_pk_add_f32 v[8:9], v[8:9], v[136:137]
	v_cvt_pk_bf16_f32 v15, v8, v9
	v_lshlrev_b32_e32 v8, 16, v32
	v_and_b32_e32 v9, 0xffff0000, v32
	v_lshlrev_b32_e32 v136, 16, v48
	v_and_b32_e32 v137, 0xffff0000, v48
	v_pk_add_f32 v[8:9], v[8:9], v[136:137]
	v_cvt_pk_bf16_f32 v16, v8, v9
	v_lshlrev_b32_e32 v8, 16, v33
	v_and_b32_e32 v9, 0xffff0000, v33
	v_lshlrev_b32_e32 v136, 16, v49
	v_and_b32_e32 v137, 0xffff0000, v49
	v_pk_add_f32 v[8:9], v[8:9], v[136:137]
	v_cvt_pk_bf16_f32 v17, v8, v9
; #define MFMA16(a, b, c) __builtin_amdgcn_mfma_f32_16x16x32_bf16((a), (b), (c), 0, 0, 0)
; __device__ __forceinline__ float bf_lo(unsigned w) { return __uint_as_float(w << 16); }
; __device__ __forceinline__ float bf_hi(unsigned w) { return __uint_as_float(w & 0xffff0000u); }
; __device__ __forceinline__ unsigned pk2(float lo, float hi) { return pg8::cvt_pk_bf16(lo, hi); }
; __device__ __forceinline__ void xattn_prompt_item(const bf16_t* xq, const bf16_t* xq1, const bf16_t* memkv, const bf16_t* memvt, bf16_t* xo, int l, int it, int lane) {
;     ...
;         u32x4 w; w.x = pk2(bf_lo(a.x) + bf_lo(c.x), bf_hi(a.x) + bf_hi(c.x)); w.y = pk2(bf_lo(a.y) + bf_lo(c.y), bf_hi(a.y) + bf_hi(c.y));
;         w.z = pk2(bf_lo(a.z) + bf_lo(c.z), bf_hi(a.z) + bf_hi(c.z)); w.w = pk2(bf_lo(a.w) + bf_lo(c.w), bf_hi(a.w) + bf_hi(c.w));
;         qf[ks] = as_bf16x8(w);
;     }
;     f32x4 sc[16];
;     float mx = -1e30f;
; #pragma unroll
;     for (int kt = 0; kt < 16; ++kt) {
;         const bf16_t* kp = memkv + ((size_t)b * 256 + 16 * kt + l15) * 4096 + l * 1024 + h * 128 + 8 * g;
;         f32x4 a = {0.f, 0.f, 0.f, 0.f};
; #pragma unroll
;         for (int ks = 0; ks < 4; ++ks) a = MFMA16(*(const bf16x8*)(kp + 32 * ks), qf[ks], a);
;         a = a * 0.08838834764831845f;
;         sc[kt] = a; mx = fmaxf(fmaxf(mx, fmaxf(a[0], a[1])), fmaxf(a[2], a[3]));
	v_lshlrev_b32_e32 v8, 16, v34
	v_and_b32_e32 v9, 0xffff0000, v34
	v_lshlrev_b32_e32 v136, 16, v50
	v_and_b32_e32 v137, 0xffff0000, v50
	v_pk_add_f32 v[8:9], v[8:9], v[136:137]
	v_cvt_pk_bf16_f32 v18, v8, v9
	v_lshlrev_b32_e32 v8, 16, v35
	v_and_b32_e32 v9, 0xffff0000, v35
	v_lshlrev_b32_e32 v136, 16, v51
	v_and_b32_e32 v137, 0xffff0000, v51
	v_pk_add_f32 v[8:9], v[8:9], v[136:137]
	v_cvt_pk_bf16_f32 v19, v8, v9
	v_lshlrev_b32_e32 v8, 16, v36
	v_and_b32_e32 v9, 0xffff0000, v36
	v_lshlrev_b32_e32 v136, 16, v52
	v_and_b32_e32 v137, 0xffff0000, v52
	v_pk_add_f32 v[8:9], v[8:9], v[136:137]
	v_cvt_pk_bf16_f32 v20, v8, v9
	v_lshlrev_b32_e32 v8, 16, v37
	v_and_b32_e32 v9, 0xffff0000, v37
	v_lshlrev_b32_e32 v136, 16, v53
	v_and_b32_e32 v137, 0xffff0000, v53
	v_pk_add_f32 v[8:9], v[8:9], v[136:137]
	v_cvt_pk_bf16_f32 v21, v8, v9
	v_lshlrev_b32_e32 v8, 16, v38
	v_and_b32_e32 v9, 0xffff0000, v38
	v_lshlrev_b32_e32 v136, 16, v54
	v_and_b32_e32 v137, 0xffff0000, v54
	v_pk_add_f32 v[8:9], v[8:9], v[136:137]
	v_cvt_pk_bf16_f32 v22, v8, v9
	v_lshlrev_b32_e32 v8, 16, v39
	v_and_b32_e32 v9, 0xffff0000, v39
	v_lshlrev_b32_e32 v136, 16, v55
	v_and_b32_e32 v137, 0xffff0000, v55
	v_pk_add_f32 v[8:9], v[8:9], v[136:137]
	v_cvt_pk_bf16_f32 v23, v8, v9
	v_lshlrev_b32_e32 v8, 16, v40
	v_and_b32_e32 v9, 0xffff0000, v40
	v_lshlrev_b32_e32 v136, 16, v56
	v_and_b32_e32 v137, 0xffff0000, v56
	v_pk_add_f32 v[8:9], v[8:9], v[136:137]
	v_cvt_pk_bf16_f32 v24, v8, v9
	v_lshlrev_b32_e32 v8, 16, v41
	v_and_b32_e32 v9, 0xffff0000, v41
	v_lshlrev_b32_e32 v136, 16, v57
	v_and_b32_e32 v137, 0xffff0000, v57
	v_pk_add_f32 v[8:9], v[8:9], v[136:137]
	v_cvt_pk_bf16_f32 v25, v8, v9
	s_waitcnt vmcnt(15)
	ds_write_b128 v59, v[146:149] offset:0
	s_waitcnt vmcnt(14)
	ds_write_b128 v59, v[150:153] offset:8704
	s_waitcnt vmcnt(13)
	ds_write_b128 v59, v[154:157] offset:17408
	s_waitcnt vmcnt(12)
	ds_write_b128 v59, v[158:161] offset:26112
	s_waitcnt vmcnt(11)
	ds_write_b128 v59, v[162:165] offset:34816
	s_waitcnt vmcnt(10)
	ds_write_b128 v59, v[166:169] offset:43520
	s_waitcnt vmcnt(9)
	ds_write_b128 v59, v[170:173] offset:52224
	s_waitcnt vmcnt(8)
	ds_write_b128 v59, v[174:177] offset:60928
	s_waitcnt vmcnt(7)
	ds_write_b128 v61, v[178:181] offset:0
	s_waitcnt vmcnt(6)
	ds_write_b128 v61, v[182:185] offset:8448
	s_waitcnt vmcnt(5)
	ds_write_b128 v61, v[186:189] offset:16896
	s_waitcnt vmcnt(4)
	ds_write_b128 v61, v[190:193] offset:25344
	s_waitcnt vmcnt(3)
	ds_write_b128 v61, v[194:197] offset:33792
	s_waitcnt vmcnt(2)
	ds_write_b128 v61, v[198:201] offset:42240
	s_waitcnt vmcnt(1)
	ds_write_b128 v61, v[202:205] offset:50688
	s_waitcnt vmcnt(0)
	ds_write_b128 v61, v[206:209] offset:59136
	s_waitcnt lgkmcnt(0)
	s_barrier
	v_mov_b32_e32 v63, 0xf149f2ca
	ds_read_b128 v[146:149], v3 offset:0
	ds_read_b128 v[150:153], v3 offset:64
	ds_read_b128 v[154:157], v3 offset:128
	ds_read_b128 v[158:161], v3 offset:192
	ds_read_b128 v[162:165], v3 offset:4352
	ds_read_b128 v[166:169], v3 offset:4416
	ds_read_b128 v[170:173], v3 offset:4480
	ds_read_b128 v[174:177], v3 offset:4544
	ds_read_b128 v[178:181], v3 offset:8704
	ds_read_b128 v[182:185], v3 offset:8768
	ds_read_b128 v[186:189], v3 offset:8832
	ds_read_b128 v[190:193], v3 offset:8896
	s_waitcnt lgkmcnt(4)
	v_mfma_f32_16x16x32_bf16 v[64:67], v[146:149], v[10:13], 0
	v_mfma_f32_16x16x32_bf16 v[68:71], v[162:165], v[10:13], 0
	ds_read_b128 v[194:197], v3 offset:13056
	v_mfma_f32_16x16x32_bf16 v[64:67], v[150:153], v[14:17], v[64:67]
	v_mfma_f32_16x16x32_bf16 v[68:71], v[166:169], v[14:17], v[68:71]
	ds_read_b128 v[198:201], v3 offset:13120
	v_mfma_f32_16x16x32_bf16 v[64:67], v[154:157], v[18:21], v[64:67]
	v_mfma_f32_16x16x32_bf16 v[68:71], v[170:173], v[18:21], v[68:71]
	ds_read_b128 v[202:205], v3 offset:13184
	v_mfma_f32_16x16x32_bf16 v[64:67], v[158:161], v[22:25], v[64:67]
	v_mfma_f32_16x16x32_bf16 v[68:71], v[174:177], v[22:25], v[68:71]
	ds_read_b128 v[206:209], v3 offset:13248
	ds_read_b128 v[146:149], v3 offset:17408
	ds_read_b128 v[150:153], v3 offset:17472
	ds_read_b128 v[154:157], v3 offset:17536
	ds_read_b128 v[158:161], v3 offset:17600
	s_waitcnt lgkmcnt(4)
	v_mfma_f32_16x16x32_bf16 v[72:75], v[178:181], v[10:13], 0
	v_mfma_f32_16x16x32_bf16 v[76:79], v[194:197], v[10:13], 0
	ds_read_b128 v[162:165], v3 offset:21760
	v_mfma_f32_16x16x32_bf16 v[72:75], v[182:185], v[14:17], v[72:75]
	v_mfma_f32_16x16x32_bf16 v[76:79], v[198:201], v[14:17], v[76:79]
	ds_read_b128 v[166:169], v3 offset:21824
	v_mfma_f32_16x16x32_bf16 v[72:75], v[186:189], v[18:21], v[72:75]
	v_mfma_f32_16x16x32_bf16 v[76:79], v[202:205], v[18:21], v[76:79]
	ds_read_b128 v[170:173], v3 offset:21888
	v_mfma_f32_16x16x32_bf16 v[72:75], v[190:193], v[22:25], v[72:75]
	v_mfma_f32_16x16x32_bf16 v[76:79], v[206:209], v[22:25], v[76:79]
	ds_read_b128 v[174:177], v3 offset:21952
	v_pk_mul_f32 v[64:65], v[64:65], s[86:87] op_sel_hi:[1,0]
	v_pk_mul_f32 v[66:67], v[66:67], s[86:87] op_sel_hi:[1,0]
	v_max3_f32 v63, v63, v64, v65
	v_max3_f32 v63, v63, v66, v67
	v_pk_mul_f32 v[68:69], v[68:69], s[86:87] op_sel_hi:[1,0]
	v_pk_mul_f32 v[70:71], v[70:71], s[86:87] op_sel_hi:[1,0]
	v_max3_f32 v63, v63, v68, v69
	v_max3_f32 v63, v63, v70, v71
	ds_read_b128 v[178:181], v3 offset:26112
	ds_read_b128 v[182:185], v3 offset:26176
	ds_read_b128 v[186:189], v3 offset:26240
	ds_read_b128 v[190:193], v3 offset:26304
	s_waitcnt lgkmcnt(4)
; #define MFMA16(a, b, c) __builtin_amdgcn_mfma_f32_16x16x32_bf16((a), (b), (c), 0, 0, 0)
; __device__ __forceinline__ void xattn_prompt_item(const bf16_t* xq, const bf16_t* xq1, const bf16_t* memkv, const bf16_t* memvt, bf16_t* xo, int l, int it, int lane) {
;     ...
;     for (int kt = 0; kt < 16; ++kt) {
;         const bf16_t* kp = memkv + ((size_t)b * 256 + 16 * kt + l15) * 4096 + l * 1024 + h * 128 + 8 * g;
;         f32x4 a = {0.f, 0.f, 0.f, 0.f};
; #pragma unroll
;         for (int ks = 0; ks < 4; ++ks) a = MFMA16(*(const bf16x8*)(kp + 32 * ks), qf[ks], a);
;         a = a * 0.08838834764831845f;
;         sc[kt] = a; mx = fmaxf(fmaxf(mx, fmaxf(a[0], a[1])), fmaxf(a[2], a[3]));
	v_mfma_f32_16x16x32_bf16 v[80:83], v[146:149], v[10:13], 0
	v_mfma_f32_16x16x32_bf16 v[84:87], v[162:165], v[10:13], 0
	ds_read_b128 v[194:197], v3 offset:30464
	v_mfma_f32_16x16x32_bf16 v[80:83], v[150:153], v[14:17], v[80:83]
	v_mfma_f32_16x16x32_bf16 v[84:87], v[166:169], v[14:17], v[84:87]
	ds_read_b128 v[198:201], v3 offset:30528
	v_mfma_f32_16x16x32_bf16 v[80:83], v[154:157], v[18:21], v[80:83]
	v_mfma_f32_16x16x32_bf16 v[84:87], v[170:173], v[18:21], v[84:87]
	ds_read_b128 v[202:205], v3 offset:30592
	v_mfma_f32_16x16x32_bf16 v[80:83], v[158:161], v[22:25], v[80:83]
	v_mfma_f32_16x16x32_bf16 v[84:87], v[174:177], v[22:25], v[84:87]
	ds_read_b128 v[206:209], v3 offset:30656
	v_pk_mul_f32 v[72:73], v[72:73], s[86:87] op_sel_hi:[1,0]
	v_pk_mul_f32 v[74:75], v[74:75], s[86:87] op_sel_hi:[1,0]
	v_max3_f32 v63, v63, v72, v73
	v_max3_f32 v63, v63, v74, v75
	v_pk_mul_f32 v[76:77], v[76:77], s[86:87] op_sel_hi:[1,0]
	v_pk_mul_f32 v[78:79], v[78:79], s[86:87] op_sel_hi:[1,0]
	v_max3_f32 v63, v63, v76, v77
	v_max3_f32 v63, v63, v78, v79
	ds_read_b128 v[146:149], v3 offset:34816
	ds_read_b128 v[150:153], v3 offset:34880
	ds_read_b128 v[154:157], v3 offset:34944
	ds_read_b128 v[158:161], v3 offset:35008
	s_waitcnt lgkmcnt(4)
	v_mfma_f32_16x16x32_bf16 v[88:91], v[178:181], v[10:13], 0
	v_mfma_f32_16x16x32_bf16 v[92:95], v[194:197], v[10:13], 0
	ds_read_b128 v[162:165], v3 offset:39168
	v_mfma_f32_16x16x32_bf16 v[88:91], v[182:185], v[14:17], v[88:91]
	v_mfma_f32_16x16x32_bf16 v[92:95], v[198:201], v[14:17], v[92:95]
	ds_read_b128 v[166:169], v3 offset:39232
	v_mfma_f32_16x16x32_bf16 v[88:91], v[186:189], v[18:21], v[88:91]
	v_mfma_f32_16x16x32_bf16 v[92:95], v[202:205], v[18:21], v[92:95]
	ds_read_b128 v[170:173], v3 offset:39296
	v_mfma_f32_16x16x32_bf16 v[88:91], v[190:193], v[22:25], v[88:91]
	v_mfma_f32_16x16x32_bf16 v[92:95], v[206:209], v[22:25], v[92:95]
	ds_read_b128 v[174:177], v3 offset:39360
	v_pk_mul_f32 v[80:81], v[80:81], s[86:87] op_sel_hi:[1,0]
	v_pk_mul_f32 v[82:83], v[82:83], s[86:87] op_sel_hi:[1,0]
	v_max3_f32 v63, v63, v80, v81
	v_max3_f32 v63, v63, v82, v83
	v_pk_mul_f32 v[84:85], v[84:85], s[86:87] op_sel_hi:[1,0]
	v_pk_mul_f32 v[86:87], v[86:87], s[86:87] op_sel_hi:[1,0]
	v_max3_f32 v63, v63, v84, v85
	v_max3_f32 v63, v63, v86, v87
	ds_read_b128 v[178:181], v3 offset:43520
	ds_read_b128 v[182:185], v3 offset:43584
	ds_read_b128 v[186:189], v3 offset:43648
	ds_read_b128 v[190:193], v3 offset:43712
	s_waitcnt lgkmcnt(4)
	v_mfma_f32_16x16x32_bf16 v[96:99], v[146:149], v[10:13], 0
	v_mfma_f32_16x16x32_bf16 v[100:103], v[162:165], v[10:13], 0
	ds_read_b128 v[194:197], v3 offset:47872
	v_mfma_f32_16x16x32_bf16 v[96:99], v[150:153], v[14:17], v[96:99]
	v_mfma_f32_16x16x32_bf16 v[100:103], v[166:169], v[14:17], v[100:103]
	ds_read_b128 v[198:201], v3 offset:47936
	v_mfma_f32_16x16x32_bf16 v[96:99], v[154:157], v[18:21], v[96:99]
	v_mfma_f32_16x16x32_bf16 v[100:103], v[170:173], v[18:21], v[100:103]
	ds_read_b128 v[202:205], v3 offset:48000
	v_mfma_f32_16x16x32_bf16 v[96:99], v[158:161], v[22:25], v[96:99]
	v_mfma_f32_16x16x32_bf16 v[100:103], v[174:177], v[22:25], v[100:103]
	ds_read_b128 v[206:209], v3 offset:48064
	v_pk_mul_f32 v[88:89], v[88:89], s[86:87] op_sel_hi:[1,0]
	v_pk_mul_f32 v[90:91], v[90:91], s[86:87] op_sel_hi:[1,0]
	v_max3_f32 v63, v63, v88, v89
	v_max3_f32 v63, v63, v90, v91
	v_pk_mul_f32 v[92:93], v[92:93], s[86:87] op_sel_hi:[1,0]
	v_pk_mul_f32 v[94:95], v[94:95], s[86:87] op_sel_hi:[1,0]
	v_max3_f32 v63, v63, v92, v93
	v_max3_f32 v63, v63, v94, v95
	ds_read_b128 v[146:149], v3 offset:52224
	ds_read_b128 v[150:153], v3 offset:52288
	ds_read_b128 v[154:157], v3 offset:52352
	ds_read_b128 v[158:161], v3 offset:52416
	s_waitcnt lgkmcnt(4)
	v_mfma_f32_16x16x32_bf16 v[104:107], v[178:181], v[10:13], 0
	v_mfma_f32_16x16x32_bf16 v[108:111], v[194:197], v[10:13], 0
	ds_read_b128 v[162:165], v3 offset:56576
	v_mfma_f32_16x16x32_bf16 v[104:107], v[182:185], v[14:17], v[104:107]
	v_mfma_f32_16x16x32_bf16 v[108:111], v[198:201], v[14:17], v[108:111]
	ds_read_b128 v[166:169], v3 offset:56640
	v_mfma_f32_16x16x32_bf16 v[104:107], v[186:189], v[18:21], v[104:107]
	v_mfma_f32_16x16x32_bf16 v[108:111], v[202:205], v[18:21], v[108:111]
	ds_read_b128 v[170:173], v3 offset:56704
	v_mfma_f32_16x16x32_bf16 v[104:107], v[190:193], v[22:25], v[104:107]
	v_mfma_f32_16x16x32_bf16 v[108:111], v[206:209], v[22:25], v[108:111]
	ds_read_b128 v[174:177], v3 offset:56768
	v_pk_mul_f32 v[96:97], v[96:97], s[86:87] op_sel_hi:[1,0]
	v_pk_mul_f32 v[98:99], v[98:99], s[86:87] op_sel_hi:[1,0]
	v_max3_f32 v63, v63, v96, v97
	v_max3_f32 v63, v63, v98, v99
	v_pk_mul_f32 v[100:101], v[100:101], s[86:87] op_sel_hi:[1,0]
	v_pk_mul_f32 v[102:103], v[102:103], s[86:87] op_sel_hi:[1,0]
	v_max3_f32 v63, v63, v100, v101
	v_max3_f32 v63, v63, v102, v103
	ds_read_b128 v[178:181], v3 offset:60928
	ds_read_b128 v[182:185], v3 offset:60992
	ds_read_b128 v[186:189], v3 offset:61056
	ds_read_b128 v[190:193], v3 offset:61120
	s_waitcnt lgkmcnt(4)
; #define MFMA16(a, b, c) __builtin_amdgcn_mfma_f32_16x16x32_bf16((a), (b), (c), 0, 0, 0)
; __device__ __forceinline__ void xattn_prompt_item(const bf16_t* xq, const bf16_t* xq1, const bf16_t* memkv, const bf16_t* memvt, bf16_t* xo, int l, int it, int lane) {
;     ...
;     for (int kt = 0; kt < 16; ++kt) {
;         const bf16_t* kp = memkv + ((size_t)b * 256 + 16 * kt + l15) * 4096 + l * 1024 + h * 128 + 8 * g;
;         f32x4 a = {0.f, 0.f, 0.f, 0.f};
; #pragma unroll
;         for (int ks = 0; ks < 4; ++ks) a = MFMA16(*(const bf16x8*)(kp + 32 * ks), qf[ks], a);
;         a = a * 0.08838834764831845f;
;         sc[kt] = a; mx = fmaxf(fmaxf(mx, fmaxf(a[0], a[1])), fmaxf(a[2], a[3]));
;     }
;     mx = fmaxf(mx, __shfl_xor(mx, 16)); mx = fmaxf(mx, __shfl_xor(mx, 32));
;     float sum = 0.f;
; #pragma unroll
;     for (int kt = 0; kt < 16; ++kt)
; #pragma unroll
;         for (int j = 0; j < 4; ++j) { const float p = __expf(sc[kt][j] - mx); sc[kt][j] = p; sum += p; }
	v_mfma_f32_16x16x32_bf16 v[112:115], v[146:149], v[10:13], 0
	v_mfma_f32_16x16x32_bf16 v[116:119], v[162:165], v[10:13], 0
	ds_read_b128 v[194:197], v3 offset:65280
	v_mfma_f32_16x16x32_bf16 v[112:115], v[150:153], v[14:17], v[112:115]
	v_mfma_f32_16x16x32_bf16 v[116:119], v[166:169], v[14:17], v[116:119]
	ds_read_b128 v[198:201], v3 offset:65344
	v_mfma_f32_16x16x32_bf16 v[112:115], v[154:157], v[18:21], v[112:115]
	v_mfma_f32_16x16x32_bf16 v[116:119], v[170:173], v[18:21], v[116:119]
	ds_read_b128 v[202:205], v3 offset:65408
	v_mfma_f32_16x16x32_bf16 v[112:115], v[158:161], v[22:25], v[112:115]
	v_mfma_f32_16x16x32_bf16 v[116:119], v[174:177], v[22:25], v[116:119]
	ds_read_b128 v[206:209], v3 offset:65472
	v_pk_mul_f32 v[104:105], v[104:105], s[86:87] op_sel_hi:[1,0]
	v_pk_mul_f32 v[106:107], v[106:107], s[86:87] op_sel_hi:[1,0]
	v_max3_f32 v63, v63, v104, v105
	v_max3_f32 v63, v63, v106, v107
	v_pk_mul_f32 v[108:109], v[108:109], s[86:87] op_sel_hi:[1,0]
	v_pk_mul_f32 v[110:111], v[110:111], s[86:87] op_sel_hi:[1,0]
	v_max3_f32 v63, v63, v108, v109
	v_max3_f32 v63, v63, v110, v111
	ds_read_b128 v[146:149], v4 offset:0
	ds_read_b128 v[150:153], v4 offset:8448
	ds_read_b128 v[154:157], v4 offset:16896
	ds_read_b128 v[158:161], v4 offset:25344
	s_waitcnt lgkmcnt(4)
	v_mfma_f32_16x16x32_bf16 v[120:123], v[178:181], v[10:13], 0
	v_mfma_f32_16x16x32_bf16 v[124:127], v[194:197], v[10:13], 0
	ds_read_b128 v[162:165], v4 offset:33792
	v_mfma_f32_16x16x32_bf16 v[120:123], v[182:185], v[14:17], v[120:123]
	v_mfma_f32_16x16x32_bf16 v[124:127], v[198:201], v[14:17], v[124:127]
	ds_read_b128 v[166:169], v4 offset:42240
	v_mfma_f32_16x16x32_bf16 v[120:123], v[186:189], v[18:21], v[120:123]
	v_mfma_f32_16x16x32_bf16 v[124:127], v[202:205], v[18:21], v[124:127]
	ds_read_b128 v[170:173], v4 offset:50688
	v_mfma_f32_16x16x32_bf16 v[120:123], v[190:193], v[22:25], v[120:123]
	v_mfma_f32_16x16x32_bf16 v[124:127], v[206:209], v[22:25], v[124:127]
	ds_read_b128 v[174:177], v4 offset:59136
	v_pk_mul_f32 v[112:113], v[112:113], s[86:87] op_sel_hi:[1,0]
	v_pk_mul_f32 v[114:115], v[114:115], s[86:87] op_sel_hi:[1,0]
	v_max3_f32 v63, v63, v112, v113
	v_max3_f32 v63, v63, v114, v115
	v_pk_mul_f32 v[116:117], v[116:117], s[86:87] op_sel_hi:[1,0]
	v_pk_mul_f32 v[118:119], v[118:119], s[86:87] op_sel_hi:[1,0]
	v_max3_f32 v63, v63, v116, v117
	v_max3_f32 v63, v63, v118, v119
	s_nop 7
	v_pk_mul_f32 v[120:121], v[120:121], s[86:87] op_sel_hi:[1,0]
	v_pk_mul_f32 v[122:123], v[122:123], s[86:87] op_sel_hi:[1,0]
	v_max3_f32 v63, v63, v120, v121
	v_max3_f32 v63, v63, v122, v123
	v_pk_mul_f32 v[124:125], v[124:125], s[86:87] op_sel_hi:[1,0]
	v_pk_mul_f32 v[126:127], v[126:127], s[86:87] op_sel_hi:[1,0]
	v_max3_f32 v63, v63, v124, v125
	v_max3_f32 v63, v63, v126, v127
	ds_bpermute_b32 v8, v6, v63
	s_waitcnt lgkmcnt(0)
	v_max_f32_e32 v8, v8, v8
	v_max_f32_e32 v63, v63, v8
	ds_bpermute_b32 v8, v7, v63
	s_waitcnt lgkmcnt(0)
	v_max_f32_e32 v8, v8, v8
	v_max_f32_e32 v63, v63, v8
	v_mov_b32_e32 v62, 0
	v_sub_f32_e32 v64, v64, v63
	v_mul_f32_e32 v64, 0x3fb8aa3b, v64
	v_exp_f32_e32 v64, v64
	v_sub_f32_e32 v65, v65, v63
	v_mul_f32_e32 v65, 0x3fb8aa3b, v65
	v_exp_f32_e32 v65, v65
	v_add_f32_e32 v62, v64, v62
	v_sub_f32_e32 v66, v66, v63
	v_mul_f32_e32 v66, 0x3fb8aa3b, v66
	v_exp_f32_e32 v66, v66
	v_add_f32_e32 v62, v65, v62
	v_sub_f32_e32 v67, v67, v63
	v_mul_f32_e32 v67, 0x3fb8aa3b, v67
	v_exp_f32_e32 v67, v67
	v_add_f32_e32 v62, v66, v62
	v_sub_f32_e32 v68, v68, v63
	v_mul_f32_e32 v68, 0x3fb8aa3b, v68
	v_exp_f32_e32 v68, v68
	v_add_f32_e32 v62, v67, v62
	v_sub_f32_e32 v69, v69, v63
	v_mul_f32_e32 v69, 0x3fb8aa3b, v69
	v_exp_f32_e32 v69, v69
	v_add_f32_e32 v62, v68, v62
	v_sub_f32_e32 v70, v70, v63
	v_mul_f32_e32 v70, 0x3fb8aa3b, v70
	v_exp_f32_e32 v70, v70
	v_add_f32_e32 v62, v69, v62
	v_sub_f32_e32 v71, v71, v63
	v_mul_f32_e32 v71, 0x3fb8aa3b, v71
	v_exp_f32_e32 v71, v71
	v_add_f32_e32 v62, v70, v62
	v_sub_f32_e32 v72, v72, v63
	v_mul_f32_e32 v72, 0x3fb8aa3b, v72
	v_exp_f32_e32 v72, v72
	v_add_f32_e32 v62, v71, v62
	v_sub_f32_e32 v73, v73, v63
	v_mul_f32_e32 v73, 0x3fb8aa3b, v73
	v_exp_f32_e32 v73, v73
	v_add_f32_e32 v62, v72, v62
	v_sub_f32_e32 v74, v74, v63
	v_mul_f32_e32 v74, 0x3fb8aa3b, v74
	v_exp_f32_e32 v74, v74
	v_add_f32_e32 v62, v73, v62
	v_sub_f32_e32 v75, v75, v63
	v_mul_f32_e32 v75, 0x3fb8aa3b, v75
	v_exp_f32_e32 v75, v75
	v_add_f32_e32 v62, v74, v62
	v_sub_f32_e32 v76, v76, v63
	v_mul_f32_e32 v76, 0x3fb8aa3b, v76
	v_exp_f32_e32 v76, v76
	v_add_f32_e32 v62, v75, v62
	v_sub_f32_e32 v77, v77, v63
	v_mul_f32_e32 v77, 0x3fb8aa3b, v77
	v_exp_f32_e32 v77, v77
	v_add_f32_e32 v62, v76, v62
	v_sub_f32_e32 v78, v78, v63
	v_mul_f32_e32 v78, 0x3fb8aa3b, v78
	v_exp_f32_e32 v78, v78
	v_add_f32_e32 v62, v77, v62
	v_sub_f32_e32 v79, v79, v63
	v_mul_f32_e32 v79, 0x3fb8aa3b, v79
	v_exp_f32_e32 v79, v79
	v_add_f32_e32 v62, v78, v62
	v_sub_f32_e32 v80, v80, v63
	v_mul_f32_e32 v80, 0x3fb8aa3b, v80
	v_exp_f32_e32 v80, v80
	v_add_f32_e32 v62, v79, v62
	v_sub_f32_e32 v81, v81, v63
	v_mul_f32_e32 v81, 0x3fb8aa3b, v81
	v_exp_f32_e32 v81, v81
	v_add_f32_e32 v62, v80, v62
	v_sub_f32_e32 v82, v82, v63
	v_mul_f32_e32 v82, 0x3fb8aa3b, v82
	v_exp_f32_e32 v82, v82
	v_add_f32_e32 v62, v81, v62
	v_sub_f32_e32 v83, v83, v63
	v_mul_f32_e32 v83, 0x3fb8aa3b, v83
	v_exp_f32_e32 v83, v83
	v_add_f32_e32 v62, v82, v62
	v_sub_f32_e32 v84, v84, v63
	v_mul_f32_e32 v84, 0x3fb8aa3b, v84
	v_exp_f32_e32 v84, v84
	v_add_f32_e32 v62, v83, v62
	v_sub_f32_e32 v85, v85, v63
	v_mul_f32_e32 v85, 0x3fb8aa3b, v85
	v_exp_f32_e32 v85, v85
	v_add_f32_e32 v62, v84, v62
	v_sub_f32_e32 v86, v86, v63
	v_mul_f32_e32 v86, 0x3fb8aa3b, v86
; __device__ __forceinline__ void xattn_prompt_item(const bf16_t* xq, const bf16_t* xq1, const bf16_t* memkv, const bf16_t* memvt, bf16_t* xo, int l, int it, int lane) {
;     ...
; #pragma unroll
;     for (int kt = 0; kt < 16; ++kt)
; #pragma unroll
;         for (int j = 0; j < 4; ++j) { const float p = __expf(sc[kt][j] - mx); sc[kt][j] = p; sum += p; }
;     sum += __shfl_xor(sum, 16); sum += __shfl_xor(sum, 32);
	v_exp_f32_e32 v86, v86
	v_add_f32_e32 v62, v85, v62
	v_sub_f32_e32 v87, v87, v63
	v_mul_f32_e32 v87, 0x3fb8aa3b, v87
	v_exp_f32_e32 v87, v87
	v_add_f32_e32 v62, v86, v62
	v_sub_f32_e32 v88, v88, v63
	v_mul_f32_e32 v88, 0x3fb8aa3b, v88
	v_exp_f32_e32 v88, v88
	v_add_f32_e32 v62, v87, v62
	v_sub_f32_e32 v89, v89, v63
	v_mul_f32_e32 v89, 0x3fb8aa3b, v89
	v_exp_f32_e32 v89, v89
	v_add_f32_e32 v62, v88, v62
	v_sub_f32_e32 v90, v90, v63
	v_mul_f32_e32 v90, 0x3fb8aa3b, v90
	v_exp_f32_e32 v90, v90
	v_add_f32_e32 v62, v89, v62
	v_sub_f32_e32 v91, v91, v63
	v_mul_f32_e32 v91, 0x3fb8aa3b, v91
	v_exp_f32_e32 v91, v91
	v_add_f32_e32 v62, v90, v62
	v_sub_f32_e32 v92, v92, v63
	v_mul_f32_e32 v92, 0x3fb8aa3b, v92
	v_exp_f32_e32 v92, v92
	v_add_f32_e32 v62, v91, v62
	v_sub_f32_e32 v93, v93, v63
	v_mul_f32_e32 v93, 0x3fb8aa3b, v93
	v_exp_f32_e32 v93, v93
	v_add_f32_e32 v62, v92, v62
	v_sub_f32_e32 v94, v94, v63
	v_mul_f32_e32 v94, 0x3fb8aa3b, v94
	v_exp_f32_e32 v94, v94
	v_add_f32_e32 v62, v93, v62
	v_sub_f32_e32 v95, v95, v63
	v_mul_f32_e32 v95, 0x3fb8aa3b, v95
	v_exp_f32_e32 v95, v95
	v_add_f32_e32 v62, v94, v62
	v_sub_f32_e32 v96, v96, v63
	v_mul_f32_e32 v96, 0x3fb8aa3b, v96
	v_exp_f32_e32 v96, v96
	v_add_f32_e32 v62, v95, v62
	v_sub_f32_e32 v97, v97, v63
	v_mul_f32_e32 v97, 0x3fb8aa3b, v97
	v_exp_f32_e32 v97, v97
	v_add_f32_e32 v62, v96, v62
	v_sub_f32_e32 v98, v98, v63
	v_mul_f32_e32 v98, 0x3fb8aa3b, v98
	v_exp_f32_e32 v98, v98
	v_add_f32_e32 v62, v97, v62
	v_sub_f32_e32 v99, v99, v63
	v_mul_f32_e32 v99, 0x3fb8aa3b, v99
	v_exp_f32_e32 v99, v99
	v_add_f32_e32 v62, v98, v62
	v_sub_f32_e32 v100, v100, v63
	v_mul_f32_e32 v100, 0x3fb8aa3b, v100
	v_exp_f32_e32 v100, v100
	v_add_f32_e32 v62, v99, v62
	v_sub_f32_e32 v101, v101, v63
	v_mul_f32_e32 v101, 0x3fb8aa3b, v101
	v_exp_f32_e32 v101, v101
	v_add_f32_e32 v62, v100, v62
	v_sub_f32_e32 v102, v102, v63
	v_mul_f32_e32 v102, 0x3fb8aa3b, v102
	v_exp_f32_e32 v102, v102
	v_add_f32_e32 v62, v101, v62
	v_sub_f32_e32 v103, v103, v63
	v_mul_f32_e32 v103, 0x3fb8aa3b, v103
	v_exp_f32_e32 v103, v103
	v_add_f32_e32 v62, v102, v62
	v_sub_f32_e32 v104, v104, v63
	v_mul_f32_e32 v104, 0x3fb8aa3b, v104
	v_exp_f32_e32 v104, v104
	v_add_f32_e32 v62, v103, v62
	v_sub_f32_e32 v105, v105, v63
	v_mul_f32_e32 v105, 0x3fb8aa3b, v105
	v_exp_f32_e32 v105, v105
	v_add_f32_e32 v62, v104, v62
	v_sub_f32_e32 v106, v106, v63
	v_mul_f32_e32 v106, 0x3fb8aa3b, v106
	v_exp_f32_e32 v106, v106
	v_add_f32_e32 v62, v105, v62
	v_sub_f32_e32 v107, v107, v63
	v_mul_f32_e32 v107, 0x3fb8aa3b, v107
	v_exp_f32_e32 v107, v107
	v_add_f32_e32 v62, v106, v62
	v_sub_f32_e32 v108, v108, v63
	v_mul_f32_e32 v108, 0x3fb8aa3b, v108
	v_exp_f32_e32 v108, v108
	v_add_f32_e32 v62, v107, v62
	v_sub_f32_e32 v109, v109, v63
	v_mul_f32_e32 v109, 0x3fb8aa3b, v109
	v_exp_f32_e32 v109, v109
	v_add_f32_e32 v62, v108, v62
	v_sub_f32_e32 v110, v110, v63
	v_mul_f32_e32 v110, 0x3fb8aa3b, v110
	v_exp_f32_e32 v110, v110
	v_add_f32_e32 v62, v109, v62
	v_sub_f32_e32 v111, v111, v63
	v_mul_f32_e32 v111, 0x3fb8aa3b, v111
	v_exp_f32_e32 v111, v111
	v_add_f32_e32 v62, v110, v62
	v_sub_f32_e32 v112, v112, v63
	v_mul_f32_e32 v112, 0x3fb8aa3b, v112
	v_exp_f32_e32 v112, v112
	v_add_f32_e32 v62, v111, v62
	v_sub_f32_e32 v113, v113, v63
	v_mul_f32_e32 v113, 0x3fb8aa3b, v113
	v_exp_f32_e32 v113, v113
	v_add_f32_e32 v62, v112, v62
	v_sub_f32_e32 v114, v114, v63
	v_mul_f32_e32 v114, 0x3fb8aa3b, v114
	v_exp_f32_e32 v114, v114
	v_add_f32_e32 v62, v113, v62
	v_sub_f32_e32 v115, v115, v63
	v_mul_f32_e32 v115, 0x3fb8aa3b, v115
	v_exp_f32_e32 v115, v115
	v_add_f32_e32 v62, v114, v62
	v_sub_f32_e32 v116, v116, v63
	v_mul_f32_e32 v116, 0x3fb8aa3b, v116
	v_exp_f32_e32 v116, v116
	v_add_f32_e32 v62, v115, v62
	v_sub_f32_e32 v117, v117, v63
	v_mul_f32_e32 v117, 0x3fb8aa3b, v117
	v_exp_f32_e32 v117, v117
	v_add_f32_e32 v62, v116, v62
	v_sub_f32_e32 v118, v118, v63
	v_mul_f32_e32 v118, 0x3fb8aa3b, v118
	v_exp_f32_e32 v118, v118
	v_add_f32_e32 v62, v117, v62
	v_sub_f32_e32 v119, v119, v63
	v_mul_f32_e32 v119, 0x3fb8aa3b, v119
	v_exp_f32_e32 v119, v119
	v_add_f32_e32 v62, v118, v62
	v_sub_f32_e32 v120, v120, v63
	v_mul_f32_e32 v120, 0x3fb8aa3b, v120
	v_exp_f32_e32 v120, v120
	v_add_f32_e32 v62, v119, v62
	v_sub_f32_e32 v121, v121, v63
	v_mul_f32_e32 v121, 0x3fb8aa3b, v121
	v_exp_f32_e32 v121, v121
	v_add_f32_e32 v62, v120, v62
	v_sub_f32_e32 v122, v122, v63
	v_mul_f32_e32 v122, 0x3fb8aa3b, v122
	v_exp_f32_e32 v122, v122
	v_add_f32_e32 v62, v121, v62
	v_sub_f32_e32 v123, v123, v63
	v_mul_f32_e32 v123, 0x3fb8aa3b, v123
	v_exp_f32_e32 v123, v123
	v_add_f32_e32 v62, v122, v62
	v_sub_f32_e32 v124, v124, v63
	v_mul_f32_e32 v124, 0x3fb8aa3b, v124
	v_exp_f32_e32 v124, v124
	v_add_f32_e32 v62, v123, v62
	v_sub_f32_e32 v125, v125, v63
	v_mul_f32_e32 v125, 0x3fb8aa3b, v125
	v_exp_f32_e32 v125, v125
	v_add_f32_e32 v62, v124, v62
	v_sub_f32_e32 v126, v126, v63
	v_mul_f32_e32 v126, 0x3fb8aa3b, v126
	v_exp_f32_e32 v126, v126
	v_add_f32_e32 v62, v125, v62
	v_sub_f32_e32 v127, v127, v63
	v_mul_f32_e32 v127, 0x3fb8aa3b, v127
	v_exp_f32_e32 v127, v127
	v_add_f32_e32 v62, v126, v62
	s_nop 0
	v_add_f32_e32 v62, v127, v62
	ds_bpermute_b32 v8, v6, v62
	s_waitcnt lgkmcnt(0)
	v_add_f32_e32 v62, v62, v8
	ds_bpermute_b32 v8, v7, v62
	s_waitcnt lgkmcnt(0)
; #define MFMA16(a, b, c) __builtin_amdgcn_mfma_f32_16x16x32_bf16((a), (b), (c), 0, 0, 0)
; __device__ __forceinline__ unsigned pk2(float lo, float hi) { return pg8::cvt_pk_bf16(lo, hi); }
; __device__ __forceinline__ void xattn_prompt_item(const bf16_t* xq, const bf16_t* xq1, const bf16_t* memkv, const bf16_t* memvt, bf16_t* xo, int l, int it, int lane) {
;     ...
;     const float inv = 1.0f / sum;
;     f32x4 o[8];
; #pragma unroll
;     for (int mi = 0; mi < 8; ++mi) o[mi] = (f32x4){0.f, 0.f, 0.f, 0.f};
; #pragma unroll
;     for (int u = 0; u < 8; ++u) {
;         u32x4 pw; pw.x = pk2(sc[2 * u][0] * inv, sc[2 * u][1] * inv); pw.y = pk2(sc[2 * u][2] * inv, sc[2 * u][3] * inv);
;         pw.z = pk2(sc[2 * u + 1][0] * inv, sc[2 * u + 1][1] * inv); pw.w = pk2(sc[2 * u + 1][2] * inv, sc[2 * u + 1][3] * inv);
;         const bf16x8 pb = as_bf16x8(pw);
;         const int pos0 = 32 * u + 4 * g;
; #pragma unroll
;         for (int mi = 0; mi < 8; ++mi) {
;             const bf16_t* vp = memvt + ((size_t)((l * 2 + b) * 512 + h * 128 + 16 * mi + l15)) * 256 + pos0;
;             const s16x4 v0 = *(const s16x4*)vp, v1 = *(const s16x4*)(vp + 16);
;             const bf16x8 va = (bf16x8){v0[0], v0[1], v0[2], v0[3], v1[0], v1[1], v1[2], v1[3]};
;             o[mi] = MFMA16(va, pb, o[mi]);
;         }
;     }
	v_add_f32_e32 v0, v62, v8
	v_div_scale_f32 v8, s[18:19], v0, v0, 1.0
	v_rcp_f32_e32 v9, v8
	s_nop 0
	v_fma_f32 v136, -v8, v9, 1.0
	v_fmac_f32_e32 v9, v136, v9
	v_div_scale_f32 v136, vcc, 1.0, v0, 1.0
	v_mul_f32_e32 v137, v136, v9
	v_fma_f32 v62, -v8, v137, v136
	v_fmac_f32_e32 v137, v62, v9
	v_fma_f32 v8, -v8, v137, v136
	v_div_fmas_f32 v8, v8, v9, v137
	v_div_fixup_f32 v62, v8, v0, 1.0
	v_pk_mul_f32 v[8:9], v[64:65], v[62:63] op_sel_hi:[1,0]
	v_cvt_pk_bf16_f32 v64, v8, v9
	v_pk_mul_f32 v[8:9], v[66:67], v[62:63] op_sel_hi:[1,0]
	v_cvt_pk_bf16_f32 v65, v8, v9
	v_pk_mul_f32 v[8:9], v[68:69], v[62:63] op_sel_hi:[1,0]
	v_cvt_pk_bf16_f32 v66, v8, v9
	v_pk_mul_f32 v[8:9], v[70:71], v[62:63] op_sel_hi:[1,0]
	v_cvt_pk_bf16_f32 v67, v8, v9
	v_pk_mul_f32 v[8:9], v[72:73], v[62:63] op_sel_hi:[1,0]
	v_cvt_pk_bf16_f32 v68, v8, v9
	v_pk_mul_f32 v[8:9], v[74:75], v[62:63] op_sel_hi:[1,0]
	v_cvt_pk_bf16_f32 v69, v8, v9
	v_pk_mul_f32 v[8:9], v[76:77], v[62:63] op_sel_hi:[1,0]
	v_cvt_pk_bf16_f32 v70, v8, v9
	v_pk_mul_f32 v[8:9], v[78:79], v[62:63] op_sel_hi:[1,0]
	v_cvt_pk_bf16_f32 v71, v8, v9
	v_pk_mul_f32 v[8:9], v[80:81], v[62:63] op_sel_hi:[1,0]
	v_cvt_pk_bf16_f32 v72, v8, v9
	v_pk_mul_f32 v[8:9], v[82:83], v[62:63] op_sel_hi:[1,0]
	v_cvt_pk_bf16_f32 v73, v8, v9
	v_pk_mul_f32 v[8:9], v[84:85], v[62:63] op_sel_hi:[1,0]
	v_cvt_pk_bf16_f32 v74, v8, v9
	v_pk_mul_f32 v[8:9], v[86:87], v[62:63] op_sel_hi:[1,0]
	v_cvt_pk_bf16_f32 v75, v8, v9
	v_pk_mul_f32 v[8:9], v[88:89], v[62:63] op_sel_hi:[1,0]
	v_cvt_pk_bf16_f32 v76, v8, v9
	v_pk_mul_f32 v[8:9], v[90:91], v[62:63] op_sel_hi:[1,0]
	v_cvt_pk_bf16_f32 v77, v8, v9
	v_pk_mul_f32 v[8:9], v[92:93], v[62:63] op_sel_hi:[1,0]
	v_cvt_pk_bf16_f32 v78, v8, v9
	v_pk_mul_f32 v[8:9], v[94:95], v[62:63] op_sel_hi:[1,0]
	v_cvt_pk_bf16_f32 v79, v8, v9
	v_pk_mul_f32 v[8:9], v[96:97], v[62:63] op_sel_hi:[1,0]
	v_cvt_pk_bf16_f32 v80, v8, v9
	v_pk_mul_f32 v[8:9], v[98:99], v[62:63] op_sel_hi:[1,0]
	v_cvt_pk_bf16_f32 v81, v8, v9
	v_pk_mul_f32 v[8:9], v[100:101], v[62:63] op_sel_hi:[1,0]
	v_cvt_pk_bf16_f32 v82, v8, v9
	v_pk_mul_f32 v[8:9], v[102:103], v[62:63] op_sel_hi:[1,0]
	v_cvt_pk_bf16_f32 v83, v8, v9
	v_pk_mul_f32 v[8:9], v[104:105], v[62:63] op_sel_hi:[1,0]
	v_cvt_pk_bf16_f32 v84, v8, v9
	v_pk_mul_f32 v[8:9], v[106:107], v[62:63] op_sel_hi:[1,0]
	v_cvt_pk_bf16_f32 v85, v8, v9
	v_pk_mul_f32 v[8:9], v[108:109], v[62:63] op_sel_hi:[1,0]
	v_cvt_pk_bf16_f32 v86, v8, v9
	v_pk_mul_f32 v[8:9], v[110:111], v[62:63] op_sel_hi:[1,0]
	v_cvt_pk_bf16_f32 v87, v8, v9
	v_pk_mul_f32 v[8:9], v[112:113], v[62:63] op_sel_hi:[1,0]
	v_cvt_pk_bf16_f32 v88, v8, v9
	v_pk_mul_f32 v[8:9], v[114:115], v[62:63] op_sel_hi:[1,0]
	v_cvt_pk_bf16_f32 v89, v8, v9
	v_pk_mul_f32 v[8:9], v[116:117], v[62:63] op_sel_hi:[1,0]
	v_cvt_pk_bf16_f32 v90, v8, v9
	v_pk_mul_f32 v[8:9], v[118:119], v[62:63] op_sel_hi:[1,0]
	v_cvt_pk_bf16_f32 v91, v8, v9
	v_pk_mul_f32 v[8:9], v[120:121], v[62:63] op_sel_hi:[1,0]
	v_cvt_pk_bf16_f32 v92, v8, v9
	v_pk_mul_f32 v[8:9], v[122:123], v[62:63] op_sel_hi:[1,0]
	v_cvt_pk_bf16_f32 v93, v8, v9
	v_pk_mul_f32 v[8:9], v[124:125], v[62:63] op_sel_hi:[1,0]
	v_cvt_pk_bf16_f32 v94, v8, v9
	v_pk_mul_f32 v[8:9], v[126:127], v[62:63] op_sel_hi:[1,0]
	v_cvt_pk_bf16_f32 v95, v8, v9
	s_nop 1
	ds_read_b128 v[178:181], v4 offset:64
	ds_read_b128 v[182:185], v4 offset:8512
	ds_read_b128 v[186:189], v4 offset:16960
	ds_read_b128 v[190:193], v4 offset:25408
	s_waitcnt lgkmcnt(4)
	v_mfma_f32_16x16x32_bf16 v[26:29], v[146:149], v[64:67], 0
	v_mfma_f32_16x16x32_bf16 v[30:33], v[150:153], v[64:67], 0
	ds_read_b128 v[194:197], v4 offset:33856
	v_mfma_f32_16x16x32_bf16 v[34:37], v[154:157], v[64:67], 0
	v_mfma_f32_16x16x32_bf16 v[38:41], v[158:161], v[64:67], 0
	ds_read_b128 v[198:201], v4 offset:42304
	v_mfma_f32_16x16x32_bf16 v[42:45], v[162:165], v[64:67], 0
	v_mfma_f32_16x16x32_bf16 v[46:49], v[166:169], v[64:67], 0
	ds_read_b128 v[202:205], v4 offset:50752
	v_mfma_f32_16x16x32_bf16 v[50:53], v[170:173], v[64:67], 0
	v_mfma_f32_16x16x32_bf16 v[54:57], v[174:177], v[64:67], 0
	ds_read_b128 v[206:209], v4 offset:59200
	ds_read_b128 v[146:149], v4 offset:128
	ds_read_b128 v[150:153], v4 offset:8576
	ds_read_b128 v[154:157], v4 offset:17024
	ds_read_b128 v[158:161], v4 offset:25472
	s_waitcnt lgkmcnt(4)
	v_mfma_f32_16x16x32_bf16 v[26:29], v[178:181], v[68:71], v[26:29]
	v_mfma_f32_16x16x32_bf16 v[30:33], v[182:185], v[68:71], v[30:33]
	ds_read_b128 v[162:165], v4 offset:33920
	v_mfma_f32_16x16x32_bf16 v[34:37], v[186:189], v[68:71], v[34:37]
	v_mfma_f32_16x16x32_bf16 v[38:41], v[190:193], v[68:71], v[38:41]
	ds_read_b128 v[166:169], v4 offset:42368
	v_mfma_f32_16x16x32_bf16 v[42:45], v[194:197], v[68:71], v[42:45]
	v_mfma_f32_16x16x32_bf16 v[46:49], v[198:201], v[68:71], v[46:49]
	ds_read_b128 v[170:173], v4 offset:50816
	v_mfma_f32_16x16x32_bf16 v[50:53], v[202:205], v[68:71], v[50:53]
	v_mfma_f32_16x16x32_bf16 v[54:57], v[206:209], v[68:71], v[54:57]
	ds_read_b128 v[174:177], v4 offset:59264
	ds_read_b128 v[178:181], v4 offset:192
	ds_read_b128 v[182:185], v4 offset:8640
	ds_read_b128 v[186:189], v4 offset:17088
	ds_read_b128 v[190:193], v4 offset:25536
	s_waitcnt lgkmcnt(4)
; #define MFMA16(a, b, c) __builtin_amdgcn_mfma_f32_16x16x32_bf16((a), (b), (c), 0, 0, 0)
; __device__ __forceinline__ unsigned pk2(float lo, float hi) { return pg8::cvt_pk_bf16(lo, hi); }
; __device__ __forceinline__ void xattn_prompt_item(const bf16_t* xq, const bf16_t* xq1, const bf16_t* memkv, const bf16_t* memvt, bf16_t* xo, int l, int it, int lane) {
;     ...
;         for (int mi = 0; mi < 8; ++mi) {
;             const bf16_t* vp = memvt + ((size_t)((l * 2 + b) * 512 + h * 128 + 16 * mi + l15)) * 256 + pos0;
;             const s16x4 v0 = *(const s16x4*)vp, v1 = *(const s16x4*)(vp + 16);
;             const bf16x8 va = (bf16x8){v0[0], v0[1], v0[2], v0[3], v1[0], v1[1], v1[2], v1[3]};
;             o[mi] = MFMA16(va, pb, o[mi]);
;         }
;     }
; #pragma unroll
;     for (int mi = 0; mi < 8; ++mi) {
;         u32x2 w; w.x = pk2(o[mi][0], o[mi][1]); w.y = pk2(o[mi][2], o[mi][3]);
;         *(u32x2*)(xo + tok * 512 + h * 128 + 16 * mi + 4 * g) = w;
;     }
	v_mfma_f32_16x16x32_bf16 v[26:29], v[146:149], v[72:75], v[26:29]
	v_mfma_f32_16x16x32_bf16 v[30:33], v[150:153], v[72:75], v[30:33]
	ds_read_b128 v[194:197], v4 offset:33984
	v_mfma_f32_16x16x32_bf16 v[34:37], v[154:157], v[72:75], v[34:37]
	v_mfma_f32_16x16x32_bf16 v[38:41], v[158:161], v[72:75], v[38:41]
	ds_read_b128 v[198:201], v4 offset:42432
	v_mfma_f32_16x16x32_bf16 v[42:45], v[162:165], v[72:75], v[42:45]
	v_mfma_f32_16x16x32_bf16 v[46:49], v[166:169], v[72:75], v[46:49]
	ds_read_b128 v[202:205], v4 offset:50880
	v_mfma_f32_16x16x32_bf16 v[50:53], v[170:173], v[72:75], v[50:53]
	v_mfma_f32_16x16x32_bf16 v[54:57], v[174:177], v[72:75], v[54:57]
	ds_read_b128 v[206:209], v4 offset:59328
	ds_read_b128 v[146:149], v4 offset:256
	ds_read_b128 v[150:153], v4 offset:8704
	ds_read_b128 v[154:157], v4 offset:17152
	ds_read_b128 v[158:161], v4 offset:25600
	s_waitcnt lgkmcnt(4)
	v_mfma_f32_16x16x32_bf16 v[26:29], v[178:181], v[76:79], v[26:29]
	v_mfma_f32_16x16x32_bf16 v[30:33], v[182:185], v[76:79], v[30:33]
	ds_read_b128 v[162:165], v4 offset:34048
	v_mfma_f32_16x16x32_bf16 v[34:37], v[186:189], v[76:79], v[34:37]
	v_mfma_f32_16x16x32_bf16 v[38:41], v[190:193], v[76:79], v[38:41]
	ds_read_b128 v[166:169], v4 offset:42496
	v_mfma_f32_16x16x32_bf16 v[42:45], v[194:197], v[76:79], v[42:45]
	v_mfma_f32_16x16x32_bf16 v[46:49], v[198:201], v[76:79], v[46:49]
	ds_read_b128 v[170:173], v4 offset:50944
	v_mfma_f32_16x16x32_bf16 v[50:53], v[202:205], v[76:79], v[50:53]
	v_mfma_f32_16x16x32_bf16 v[54:57], v[206:209], v[76:79], v[54:57]
	ds_read_b128 v[174:177], v4 offset:59392
	ds_read_b128 v[178:181], v4 offset:320
	ds_read_b128 v[182:185], v4 offset:8768
	ds_read_b128 v[186:189], v4 offset:17216
	ds_read_b128 v[190:193], v4 offset:25664
	s_waitcnt lgkmcnt(4)
	v_mfma_f32_16x16x32_bf16 v[26:29], v[146:149], v[80:83], v[26:29]
	v_mfma_f32_16x16x32_bf16 v[30:33], v[150:153], v[80:83], v[30:33]
	ds_read_b128 v[194:197], v4 offset:34112
	v_mfma_f32_16x16x32_bf16 v[34:37], v[154:157], v[80:83], v[34:37]
	v_mfma_f32_16x16x32_bf16 v[38:41], v[158:161], v[80:83], v[38:41]
	ds_read_b128 v[198:201], v4 offset:42560
	v_mfma_f32_16x16x32_bf16 v[42:45], v[162:165], v[80:83], v[42:45]
	v_mfma_f32_16x16x32_bf16 v[46:49], v[166:169], v[80:83], v[46:49]
	ds_read_b128 v[202:205], v4 offset:51008
	v_mfma_f32_16x16x32_bf16 v[50:53], v[170:173], v[80:83], v[50:53]
	v_mfma_f32_16x16x32_bf16 v[54:57], v[174:177], v[80:83], v[54:57]
	ds_read_b128 v[206:209], v4 offset:59456
	ds_read_b128 v[146:149], v4 offset:384
	ds_read_b128 v[150:153], v4 offset:8832
	ds_read_b128 v[154:157], v4 offset:17280
	ds_read_b128 v[158:161], v4 offset:25728
	s_waitcnt lgkmcnt(4)
	v_mfma_f32_16x16x32_bf16 v[26:29], v[178:181], v[84:87], v[26:29]
	v_mfma_f32_16x16x32_bf16 v[30:33], v[182:185], v[84:87], v[30:33]
	ds_read_b128 v[162:165], v4 offset:34176
	v_mfma_f32_16x16x32_bf16 v[34:37], v[186:189], v[84:87], v[34:37]
	v_mfma_f32_16x16x32_bf16 v[38:41], v[190:193], v[84:87], v[38:41]
	ds_read_b128 v[166:169], v4 offset:42624
	v_mfma_f32_16x16x32_bf16 v[42:45], v[194:197], v[84:87], v[42:45]
	v_mfma_f32_16x16x32_bf16 v[46:49], v[198:201], v[84:87], v[46:49]
	ds_read_b128 v[170:173], v4 offset:51072
	v_mfma_f32_16x16x32_bf16 v[50:53], v[202:205], v[84:87], v[50:53]
	v_mfma_f32_16x16x32_bf16 v[54:57], v[206:209], v[84:87], v[54:57]
	ds_read_b128 v[174:177], v4 offset:59520
	ds_read_b128 v[178:181], v4 offset:448
	ds_read_b128 v[182:185], v4 offset:8896
	ds_read_b128 v[186:189], v4 offset:17344
	ds_read_b128 v[190:193], v4 offset:25792
	s_waitcnt lgkmcnt(4)
	v_mfma_f32_16x16x32_bf16 v[26:29], v[146:149], v[88:91], v[26:29]
	v_mfma_f32_16x16x32_bf16 v[30:33], v[150:153], v[88:91], v[30:33]
	ds_read_b128 v[194:197], v4 offset:34240
	v_mfma_f32_16x16x32_bf16 v[34:37], v[154:157], v[88:91], v[34:37]
	v_mfma_f32_16x16x32_bf16 v[38:41], v[158:161], v[88:91], v[38:41]
	ds_read_b128 v[198:201], v4 offset:42688
	v_mfma_f32_16x16x32_bf16 v[42:45], v[162:165], v[88:91], v[42:45]
	v_mfma_f32_16x16x32_bf16 v[46:49], v[166:169], v[88:91], v[46:49]
	ds_read_b128 v[202:205], v4 offset:51136
	v_mfma_f32_16x16x32_bf16 v[50:53], v[170:173], v[88:91], v[50:53]
	v_mfma_f32_16x16x32_bf16 v[54:57], v[174:177], v[88:91], v[54:57]
	ds_read_b128 v[206:209], v4 offset:59584
	s_waitcnt lgkmcnt(0)
	v_mfma_f32_16x16x32_bf16 v[26:29], v[178:181], v[92:95], v[26:29]
	v_mfma_f32_16x16x32_bf16 v[30:33], v[182:185], v[92:95], v[30:33]
	v_mfma_f32_16x16x32_bf16 v[34:37], v[186:189], v[92:95], v[34:37]
	v_mfma_f32_16x16x32_bf16 v[38:41], v[190:193], v[92:95], v[38:41]
	v_mfma_f32_16x16x32_bf16 v[42:45], v[194:197], v[92:95], v[42:45]
	v_mfma_f32_16x16x32_bf16 v[46:49], v[198:201], v[92:95], v[46:49]
	v_mfma_f32_16x16x32_bf16 v[50:53], v[202:205], v[92:95], v[50:53]
	v_mfma_f32_16x16x32_bf16 v[54:57], v[206:209], v[92:95], v[54:57]
	s_nop 7
	v_cvt_pk_bf16_f32 v8, v26, v27
	v_cvt_pk_bf16_f32 v9, v28, v29
	global_store_dwordx2 v5, v[8:9], s[4:5] offset:0
	s_nop 0
	v_cvt_pk_bf16_f32 v8, v30, v31
	v_cvt_pk_bf16_f32 v9, v32, v33
	global_store_dwordx2 v5, v[8:9], s[4:5] offset:32
	s_nop 0
	v_cvt_pk_bf16_f32 v8, v34, v35
	v_cvt_pk_bf16_f32 v9, v36, v37
	global_store_dwordx2 v5, v[8:9], s[4:5] offset:64
	s_nop 0
	v_cvt_pk_bf16_f32 v8, v38, v39
	v_cvt_pk_bf16_f32 v9, v40, v41
	global_store_dwordx2 v5, v[8:9], s[4:5] offset:96
	s_nop 0
	v_cvt_pk_bf16_f32 v8, v42, v43
	v_cvt_pk_bf16_f32 v9, v44, v45
	global_store_dwordx2 v5, v[8:9], s[4:5] offset:128
	s_nop 0
	v_cvt_pk_bf16_f32 v8, v46, v47
	v_cvt_pk_bf16_f32 v9, v48, v49
	global_store_dwordx2 v5, v[8:9], s[4:5] offset:160
	s_nop 0
	v_cvt_pk_bf16_f32 v8, v50, v51
	v_cvt_pk_bf16_f32 v9, v52, v53
	global_store_dwordx2 v5, v[8:9], s[4:5] offset:192
	s_nop 0
	v_cvt_pk_bf16_f32 v8, v54, v55
	v_cvt_pk_bf16_f32 v9, v56, v57
	global_store_dwordx2 v5, v[8:9], s[4:5] offset:224
	s_nop 0
	s_cmpk_eq_i32 s88, 0x100
	s_cselect_b32 s7, 0x80, s88
	s_add_i32 s6, s6, s7
	s_cmpk_gt_i32 s6, 0xff
	s_cbranch_scc1 .LBB0_1405
	s_barrier
	s_branch .Lxp_pair
